# best4 + nt sc1 on pool/ssm2/GLU output stores
# baseline (speedup 1.0000x reference)
; __device__ __forceinline__ float sigm(float v) { return __builtin_amdgcn_rcpf(1.0f + __builtin_amdgcn_exp2f(-LOG2E * v)); }
; __device__ __forceinline__ float bf_lo(unsigned w) { return __uint_as_float(w << 16); }
; __device__ __forceinline__ float silu_f(float v) { return v * __builtin_amdgcn_rcpf(1.0f + __builtin_amdgcn_exp2f(-1.4426950408889634f * v)); }
;     __device__ __forceinline__ void operator()(const f32x4 (&acc)[2][2][4][2], const Unit& u, int wr, int wc, int fr, int fq) const {
;         EPI_LANE();
;         const char* ygb = (const char*)(YG + (size_t)u.pm * BM * 256); const char* sgb = (const char*)(ZC + (size_t)u.pm * BM * 512 + 256); char* yb = (char*)(Y + (size_t)u.pm * BM * 1024 + 768);
;         unsigned rl0 = (unsigned)(wr * 64 + fr), col0 = (unsigned)(wc * 32 + 8 * fq); asm volatile("" : "+v"(rl0), "+v"(col0));
; #pragma unroll
;         for (int bj = 0; bj < 2; ++bj) { const unsigned col = col0 + bj * HALF;
; #pragma unroll
;             for (int ai = 0; ai < 2; ++ai) {
;                 u32x4 ygv[4], sgv[4];
; #pragma unroll
;                 for (int m = 0; m < 4; ++m) { const unsigned rl = rl0 + (unsigned)(ai * HALF + m * 16);
;                     ygv[m] = *(const u32x4*)(ygb + (rl * 256u + col) * 2u); sgv[m] = *(const u32x4*)(sgb + (rl * 512u + col) * 2u); }
; #pragma unroll
;                 for (int m = 0; m < 4; ++m) { const unsigned rl = rl0 + (unsigned)(ai * HALF + m * 16);
;                     const u32x4 yg = ygv[m], sg = sgv[m];
;                     const f32x4 v0 = acc[ai][bj][m][0], v1 = acc[ai][bj][m][1];
;                     u32x4 w;
;                     w.x = cvt_pk_bf16(bf_lo(yg.x) * sigm(v0[0]) * silu_f(bf_lo(sg.x)), bf_hi(yg.x) * sigm(v0[1]) * silu_f(bf_hi(sg.x)));
;                     w.y = cvt_pk_bf16(bf_lo(yg.y) * sigm(v0[2]) * silu_f(bf_lo(sg.y)), bf_hi(yg.y) * sigm(v0[3]) * silu_f(bf_hi(sg.y)));
;                     w.z = cvt_pk_bf16(bf_lo(yg.z) * sigm(v1[0]) * silu_f(bf_lo(sg.z)), bf_hi(yg.z) * sigm(v1[1]) * silu_f(bf_hi(sg.z)));
;                     w.w = cvt_pk_bf16(bf_lo(yg.w) * sigm(v1[2]) * silu_f(bf_lo(sg.w)), bf_hi(yg.w) * sigm(v1[3]) * silu_f(bf_hi(sg.w)));
;                     *(u32x4*)(yb + (rl * 1024u + col) * 2u) = w; }
;                 asm volatile("" : "+v"(rl0), "+v"(col0) :: "memory"); } }
.LBB0_82:
	v_readlane_b32 s20, v253, 0
	v_readlane_b32 s21, v253, 1
	s_load_dwordx4 s[76:79], s[20:21], 0xa8
	s_ashr_i32 s61, s60, 31
	s_lshl_b64 s[16:17], s[60:61], 17
	s_add_u32 s62, s90, s16
	s_addc_u32 s63, s91, s17
	s_lshl_b64 s[16:17], s[60:61], 18
	s_waitcnt lgkmcnt(0)
	s_add_u32 s6, s78, s16
	s_addc_u32 s12, s79, s17
	s_add_u32 s64, s6, 0xc000200
	v_mov_b32_e32 v106, v212
	s_addc_u32 s65, s12, 0
	s_lshl_b64 s[16:17], s[60:61], 19
	s_add_u32 s60, s82, s16
	v_readfirstlane_b32 s0, v106
	s_addc_u32 s61, s83, s17
	s_ashr_i32 s6, s0, 2
	s_andn2_b32 s6, s6, 63
	s_lshr_b32 s0, s0, 1
	v_and_or_b32 v174, v106, 15, s6
	s_and_b32 s0, s0, 0x60
	v_lshrrev_b32_e32 v106, 1, v106
	v_and_or_b32 v175, v106, 24, s0
	v_mul_f32_e32 v158, 0xbfb8aa3b, v158
	v_lshlrev_b32_e32 v176, 1, v175
	v_lshlrev_b32_e32 v106, 9, v174
	v_add_u32_e32 v107, v106, v176
	v_add_u32_e32 v177, v107, v106
	global_load_dwordx4 v[150:153], v107, s[62:63] nt
	global_load_dwordx4 v[154:157], v177, s[64:65] nt
	v_add_u32_e32 v107, 0x2000, v106
	v_add_u32_e32 v108, v107, v176
	v_add_u32_e32 v107, v108, v107
	global_load_dwordx4 v[138:141], v108, s[62:63] nt
	global_load_dwordx4 v[142:145], v107, s[64:65] nt
	v_mul_f32_e32 v159, 0xbfb8aa3b, v159
	v_exp_f32_e32 v158, v158
	v_exp_f32_e32 v159, v159
	v_mul_f32_e32 v146, 0xbfb8aa3b, v146
	v_mul_f32_e32 v147, 0xbfb8aa3b, v147
	v_add_f32_e32 v158, 1.0, v158
	v_add_f32_e32 v159, 1.0, v159
	v_rcp_f32_e32 v158, v158
	v_rcp_f32_e32 v159, v159
	v_exp_f32_e32 v146, v146
	v_exp_f32_e32 v147, v147
	v_add_u32_e32 v107, 0x4000, v106
	v_add_u32_e32 v108, v107, v176
	v_add_f32_e32 v146, 1.0, v146
	v_add_f32_e32 v147, 1.0, v147
	v_rcp_f32_e32 v146, v146
	v_rcp_f32_e32 v147, v147
	v_add_u32_e32 v107, v108, v107
	global_load_dwordx4 v[122:125], v108, s[62:63] nt
	global_load_dwordx4 v[126:129], v107, s[64:65] nt
	v_add_u32_e32 v110, 0x6000, v106
	v_add_u32_e32 v111, v110, v176
	v_add_u32_e32 v110, v111, v110
	global_load_dwordx4 v[106:109], v111, s[62:63] nt
	v_mul_f32_e32 v134, 0xbfb8aa3b, v134
	global_load_dwordx4 v[110:113], v110, s[64:65] nt
	v_mul_f32_e32 v135, 0xbfb8aa3b, v135
	v_exp_f32_e32 v134, v134
	v_exp_f32_e32 v135, v135
	v_mul_f32_e32 v130, 0xbfb8aa3b, v130
	v_mul_f32_e32 v131, 0xbfb8aa3b, v131
	v_add_f32_e32 v134, 1.0, v134
	v_add_f32_e32 v135, 1.0, v135
	v_rcp_f32_e32 v134, v134
	v_rcp_f32_e32 v135, v135
	v_exp_f32_e32 v130, v130
	v_exp_f32_e32 v131, v131
	v_mul_f32_e32 v118, 0xbfb8aa3b, v118
	v_mul_f32_e32 v119, 0xbfb8aa3b, v119
	v_add_f32_e32 v130, 1.0, v130
	v_add_f32_e32 v131, 1.0, v131
	v_rcp_f32_e32 v130, v130
	v_rcp_f32_e32 v131, v131
	v_exp_f32_e32 v118, v118
	v_exp_f32_e32 v119, v119
	v_mul_f32_e32 v114, 0xbfb8aa3b, v114
	v_mul_f32_e32 v115, 0xbfb8aa3b, v115
	v_add_f32_e32 v118, 1.0, v118
	v_add_f32_e32 v119, 1.0, v119
	v_rcp_f32_e32 v118, v118
	v_rcp_f32_e32 v119, v119
	v_exp_f32_e32 v114, v114
	v_exp_f32_e32 v115, v115
	v_mul_f32_e32 v102, 0xbfb8aa3b, v102
	v_mul_f32_e32 v103, 0xbfb8aa3b, v103
	v_add_f32_e32 v114, 1.0, v114
	v_add_f32_e32 v115, 1.0, v115
	v_rcp_f32_e32 v114, v114
	v_rcp_f32_e32 v115, v115
	v_exp_f32_e32 v102, v102
	v_exp_f32_e32 v103, v103
	v_mul_f32_e32 v98, 0xbfb8aa3b, v98
	v_mul_f32_e32 v99, 0xbfb8aa3b, v99
	v_add_f32_e32 v102, 1.0, v102
	v_add_f32_e32 v103, 1.0, v103
	v_rcp_f32_e32 v102, v102
	v_rcp_f32_e32 v103, v103
	v_exp_f32_e32 v98, v98
	v_exp_f32_e32 v99, v99
	v_mul_f32_e32 v92, 0xbfb8aa3b, v92
	v_mul_f32_e32 v93, 0xbfb8aa3b, v93
	v_add_f32_e32 v98, 1.0, v98
	v_add_f32_e32 v99, 1.0, v99
	s_waitcnt vmcnt(0)
	v_lshlrev_b32_e32 v182, 16, v150
	v_lshlrev_b32_e32 v178, 16, v154
	v_and_b32_e32 v179, 0xffff0000, v154
	v_mul_f32_e32 v154, 0xbfb8aa3b, v178
	v_and_b32_e32 v183, 0xffff0000, v150
	v_mul_f32_e32 v150, 0xbfb8aa3b, v179
	v_exp_f32_e32 v154, v154
	v_exp_f32_e32 v150, v150
	v_pk_mul_f32 v[158:159], v[158:159], v[182:183]
	v_rcp_f32_e32 v98, v98
	v_add_f32_e32 v154, 1.0, v154
	v_add_f32_e32 v150, 1.0, v150
	v_rcp_f32_e32 v180, v154
	v_rcp_f32_e32 v181, v150
	v_mul_f32_e32 v154, 0xbfb8aa3b, v160
	v_exp_f32_e32 v154, v154
	v_rcp_f32_e32 v99, v99
	v_pk_mul_f32 v[178:179], v[180:181], v[178:179]
	v_exp_f32_e32 v92, v92
	v_pk_mul_f32 v[158:159], v[158:159], v[178:179]
	v_add_f32_e32 v154, 1.0, v154
	v_cvt_pk_bf16_f32 v150, v158, v159
	v_rcp_f32_e32 v158, v154
	v_mul_f32_e32 v154, 0xbfb8aa3b, v161
	v_exp_f32_e32 v154, v154
	v_lshlrev_b32_e32 v178, 16, v151
	v_and_b32_e32 v179, 0xffff0000, v151
	v_exp_f32_e32 v93, v93
	v_add_f32_e32 v154, 1.0, v154
	v_rcp_f32_e32 v159, v154
	v_lshlrev_b32_e32 v154, 16, v155
	v_and_b32_e32 v155, 0xffff0000, v155
	v_mul_f32_e32 v160, 0xbfb8aa3b, v154
	v_mul_f32_e32 v151, 0xbfb8aa3b, v155
	v_exp_f32_e32 v160, v160
	v_exp_f32_e32 v151, v151
	v_pk_mul_f32 v[158:159], v[158:159], v[178:179]
	v_add_f32_e32 v92, 1.0, v92
	v_add_f32_e32 v160, 1.0, v160
	v_add_f32_e32 v151, 1.0, v151
	v_rcp_f32_e32 v160, v160
	v_rcp_f32_e32 v161, v151
	v_add_f32_e32 v93, 1.0, v93
	v_rcp_f32_e32 v92, v92
	v_rcp_f32_e32 v93, v93
	v_pk_mul_f32 v[154:155], v[160:161], v[154:155]
	v_lshlrev_b32_e32 v160, 16, v152
	v_pk_mul_f32 v[154:155], v[158:159], v[154:155]
	v_and_b32_e32 v161, 0xffff0000, v152
	v_cvt_pk_bf16_f32 v151, v154, v155
	v_lshlrev_b32_e32 v154, 16, v156
	v_and_b32_e32 v155, 0xffff0000, v156
	v_mul_f32_e32 v156, 0xbfb8aa3b, v154
	v_mul_f32_e32 v152, 0xbfb8aa3b, v155
	v_exp_f32_e32 v156, v156
	v_exp_f32_e32 v152, v152
	v_pk_mul_f32 v[146:147], v[146:147], v[160:161]
	v_mul_f32_e32 v88, 0xbfb8aa3b, v88
	v_add_f32_e32 v156, 1.0, v156
	v_add_f32_e32 v152, 1.0, v152
	v_rcp_f32_e32 v158, v156
	v_rcp_f32_e32 v159, v152
	v_lshlrev_b32_e32 v156, 16, v153
	v_mul_f32_e32 v89, 0xbfb8aa3b, v89
; __device__ __forceinline__ float sigm(float v) { return __builtin_amdgcn_rcpf(1.0f + __builtin_amdgcn_exp2f(-LOG2E * v)); }
; __device__ __forceinline__ float bf_lo(unsigned w) { return __uint_as_float(w << 16); }
; __device__ __forceinline__ float silu_f(float v) { return v * __builtin_amdgcn_rcpf(1.0f + __builtin_amdgcn_exp2f(-1.4426950408889634f * v)); }
; __device__ __forceinline__ float bf_hi(unsigned w) { return __uint_as_float(w & 0xffff0000u); }
; __device__ __forceinline__ unsigned cvt_pk_bf16(float lo, float hi) { f32x2_t v = {lo, hi}; bf16x2_t b = __builtin_convertvector(v, bf16x2_t); return __builtin_bit_cast(unsigned, b); }
;     __device__ __forceinline__ void operator()(const f32x4 (&acc)[2][2][4][2], const Unit& u, int wr, int wc, int fr, int fq) const {
;     ...
;                 for (int m = 0; m < 4; ++m) { const unsigned rl = rl0 + (unsigned)(ai * HALF + m * 16);
;                     const u32x4 yg = ygv[m], sg = sgv[m];
;                     const f32x4 v0 = acc[ai][bj][m][0], v1 = acc[ai][bj][m][1];
;                     u32x4 w;
;                     w.x = cvt_pk_bf16(bf_lo(yg.x) * sigm(v0[0]) * silu_f(bf_lo(sg.x)), bf_hi(yg.x) * sigm(v0[1]) * silu_f(bf_hi(sg.x)));
;                     w.y = cvt_pk_bf16(bf_lo(yg.y) * sigm(v0[2]) * silu_f(bf_lo(sg.y)), bf_hi(yg.y) * sigm(v0[3]) * silu_f(bf_hi(sg.y)));
;                     w.z = cvt_pk_bf16(bf_lo(yg.z) * sigm(v1[0]) * silu_f(bf_lo(sg.z)), bf_hi(yg.z) * sigm(v1[1]) * silu_f(bf_hi(sg.z)));
;                     w.w = cvt_pk_bf16(bf_lo(yg.w) * sigm(v1[2]) * silu_f(bf_lo(sg.w)), bf_hi(yg.w) * sigm(v1[3]) * silu_f(bf_hi(sg.w)));
;                     *(u32x4*)(yb + (rl * 1024u + col) * 2u) = w; }
	v_exp_f32_e32 v88, v88
	v_pk_mul_f32 v[154:155], v[158:159], v[154:155]
	v_exp_f32_e32 v89, v89
	v_pk_mul_f32 v[146:147], v[146:147], v[154:155]
	v_add_f32_e32 v88, 1.0, v88
	v_cvt_pk_bf16_f32 v152, v146, v147
	v_mul_f32_e32 v146, 0xbfb8aa3b, v148
	v_mul_f32_e32 v147, 0xbfb8aa3b, v149
	v_lshlrev_b32_e32 v148, 16, v157
	v_and_b32_e32 v149, 0xffff0000, v157
	v_mul_f32_e32 v154, 0xbfb8aa3b, v148
	v_and_b32_e32 v157, 0xffff0000, v153
	v_mul_f32_e32 v153, 0xbfb8aa3b, v149
	v_exp_f32_e32 v146, v146
	v_exp_f32_e32 v147, v147
	v_exp_f32_e32 v154, v154
	v_exp_f32_e32 v153, v153
	v_add_f32_e32 v146, 1.0, v146
	v_add_f32_e32 v147, 1.0, v147
	v_add_f32_e32 v154, 1.0, v154
	v_add_f32_e32 v153, 1.0, v153
	v_rcp_f32_e32 v146, v146
	v_rcp_f32_e32 v147, v147
	v_rcp_f32_e32 v154, v154
	v_rcp_f32_e32 v155, v153
	v_add_f32_e32 v89, 1.0, v89
	v_pk_mul_f32 v[146:147], v[146:147], v[156:157]
	v_rcp_f32_e32 v88, v88
	v_pk_mul_f32 v[148:149], v[154:155], v[148:149]
	v_rcp_f32_e32 v89, v89
	v_pk_mul_f32 v[146:147], v[146:147], v[148:149]
	v_lshlrev_b32_e32 v148, 16, v142
	v_cvt_pk_bf16_f32 v153, v146, v147
	v_lshl_add_u32 v146, v174, 10, v177
	v_and_b32_e32 v149, 0xffff0000, v142
	global_store_dwordx4 v146, v[150:153], s[60:61] offset:1536 nt sc1
	v_mul_f32_e32 v142, 0xbfb8aa3b, v148
	v_exp_f32_e32 v142, v142
	v_lshlrev_b32_e32 v152, 16, v138
	v_and_b32_e32 v153, 0xffff0000, v138
	v_mul_f32_e32 v138, 0xbfb8aa3b, v149
	v_exp_f32_e32 v138, v138
	v_add_f32_e32 v142, 1.0, v142
	v_rcp_f32_e32 v150, v142
	v_pk_mul_f32 v[134:135], v[134:135], v[152:153]
	v_add_f32_e32 v138, 1.0, v138
	v_rcp_f32_e32 v151, v138
	v_lshlrev_b32_e32 v142, 16, v143
	v_and_b32_e32 v143, 0xffff0000, v143
	v_mul_f32_e32 v84, 0xbfb8aa3b, v84
	v_pk_mul_f32 v[148:149], v[150:151], v[148:149]
	v_mul_f32_e32 v85, 0xbfb8aa3b, v85
	v_pk_mul_f32 v[134:135], v[134:135], v[148:149]
	v_lshlrev_b32_e32 v148, 16, v139
	v_cvt_pk_bf16_f32 v134, v134, v135
	v_mul_f32_e32 v135, 0xbfb8aa3b, v136
	v_exp_f32_e32 v135, v135
	v_and_b32_e32 v149, 0xffff0000, v139
	v_exp_f32_e32 v84, v84
	v_exp_f32_e32 v85, v85
	v_add_f32_e32 v135, 1.0, v135
	v_rcp_f32_e32 v136, v135
	v_mul_f32_e32 v135, 0xbfb8aa3b, v137
	v_exp_f32_e32 v135, v135
	v_add_f32_e32 v84, 1.0, v84
	v_add_f32_e32 v85, 1.0, v85
	v_rcp_f32_e32 v84, v84
	v_add_f32_e32 v135, 1.0, v135
	v_rcp_f32_e32 v137, v135
	v_mul_f32_e32 v135, 0xbfb8aa3b, v142
	v_exp_f32_e32 v135, v135
	v_rcp_f32_e32 v85, v85
	v_pk_mul_f32 v[136:137], v[136:137], v[148:149]
	v_mul_f32_e32 v80, 0xbfb8aa3b, v80
	v_add_f32_e32 v135, 1.0, v135
	v_rcp_f32_e32 v138, v135
	v_mul_f32_e32 v135, 0xbfb8aa3b, v143
	v_exp_f32_e32 v135, v135
	v_mul_f32_e32 v81, 0xbfb8aa3b, v81
	v_exp_f32_e32 v80, v80
	v_exp_f32_e32 v81, v81
	v_add_f32_e32 v135, 1.0, v135
	v_rcp_f32_e32 v139, v135
	v_add_f32_e32 v80, 1.0, v80
	v_add_f32_e32 v81, 1.0, v81
	v_rcp_f32_e32 v80, v80
	v_pk_mul_f32 v[138:139], v[138:139], v[142:143]
	v_lshlrev_b32_e32 v142, 16, v140
	v_pk_mul_f32 v[136:137], v[136:137], v[138:139]
	v_and_b32_e32 v143, 0xffff0000, v140
	v_cvt_pk_bf16_f32 v135, v136, v137
	v_lshlrev_b32_e32 v136, 16, v144
	v_and_b32_e32 v137, 0xffff0000, v144
	v_mul_f32_e32 v138, 0xbfb8aa3b, v136
	v_mul_f32_e32 v139, 0xbfb8aa3b, v137
	v_exp_f32_e32 v138, v138
	v_exp_f32_e32 v139, v139
	v_pk_mul_f32 v[130:131], v[130:131], v[142:143]
	v_lshlrev_b32_e32 v140, 16, v141
	v_add_f32_e32 v138, 1.0, v138
	v_add_f32_e32 v139, 1.0, v139
	v_rcp_f32_e32 v138, v138
	v_rcp_f32_e32 v139, v139
	v_and_b32_e32 v141, 0xffff0000, v141
	v_rcp_f32_e32 v81, v81
	v_mul_f32_e32 v76, 0xbfb8aa3b, v76
	v_pk_mul_f32 v[136:137], v[138:139], v[136:137]
	v_mul_f32_e32 v77, 0xbfb8aa3b, v77
	v_pk_mul_f32 v[130:131], v[130:131], v[136:137]
	v_exp_f32_e32 v76, v76
	v_cvt_pk_bf16_f32 v136, v130, v131
	v_mul_f32_e32 v130, 0xbfb8aa3b, v132
	v_lshlrev_b32_e32 v132, 16, v145
	v_mul_f32_e32 v137, 0xbfb8aa3b, v132
	v_exp_f32_e32 v137, v137
	v_mul_f32_e32 v131, 0xbfb8aa3b, v133
	v_and_b32_e32 v133, 0xffff0000, v145
	v_exp_f32_e32 v130, v130
	v_add_f32_e32 v137, 1.0, v137
	v_rcp_f32_e32 v138, v137
	v_mul_f32_e32 v137, 0xbfb8aa3b, v133
	v_exp_f32_e32 v131, v131
	v_exp_f32_e32 v137, v137
	v_add_f32_e32 v130, 1.0, v130
	v_rcp_f32_e32 v130, v130
	v_add_f32_e32 v131, 1.0, v131
	v_add_f32_e32 v137, 1.0, v137
	v_rcp_f32_e32 v131, v131
	v_rcp_f32_e32 v139, v137
	v_exp_f32_e32 v77, v77
	v_add_f32_e32 v76, 1.0, v76
	v_pk_mul_f32 v[130:131], v[130:131], v[140:141]
	v_pk_mul_f32 v[132:133], v[138:139], v[132:133]
	v_add_f32_e32 v77, 1.0, v77
	v_pk_mul_f32 v[130:131], v[130:131], v[132:133]
	v_rcp_f32_e32 v76, v76
	v_cvt_pk_bf16_f32 v137, v130, v131
	v_add_u32_e32 v130, 0x8000, v146
	global_store_dwordx4 v130, v[134:137], s[60:61] offset:1536 nt sc1
	v_lshlrev_b32_e32 v130, 16, v126
	v_and_b32_e32 v131, 0xffff0000, v126
	v_mul_f32_e32 v126, 0xbfb8aa3b, v130
	v_lshlrev_b32_e32 v134, 16, v122
	v_and_b32_e32 v135, 0xffff0000, v122
	v_mul_f32_e32 v122, 0xbfb8aa3b, v131
	v_exp_f32_e32 v126, v126
	v_exp_f32_e32 v122, v122
	v_pk_mul_f32 v[118:119], v[118:119], v[134:135]
	v_rcp_f32_e32 v77, v77
	v_add_f32_e32 v126, 1.0, v126
	v_add_f32_e32 v122, 1.0, v122
	v_rcp_f32_e32 v132, v126
	v_rcp_f32_e32 v133, v122
	v_lshlrev_b32_e32 v126, 16, v127
	v_and_b32_e32 v127, 0xffff0000, v127
	v_mul_f32_e32 v72, 0xbfb8aa3b, v72
	v_pk_mul_f32 v[130:131], v[132:133], v[130:131]
	v_mul_f32_e32 v73, 0xbfb8aa3b, v73
	v_pk_mul_f32 v[118:119], v[118:119], v[130:131]
	v_lshlrev_b32_e32 v130, 16, v123
	v_cvt_pk_bf16_f32 v118, v118, v119
	v_mul_f32_e32 v119, 0xbfb8aa3b, v120
	v_exp_f32_e32 v119, v119
	v_and_b32_e32 v131, 0xffff0000, v123
	v_exp_f32_e32 v72, v72
	v_exp_f32_e32 v73, v73
	v_add_f32_e32 v119, 1.0, v119
; __device__ __forceinline__ float sigm(float v) { return __builtin_amdgcn_rcpf(1.0f + __builtin_amdgcn_exp2f(-LOG2E * v)); }
; __device__ __forceinline__ float bf_lo(unsigned w) { return __uint_as_float(w << 16); }
; __device__ __forceinline__ float silu_f(float v) { return v * __builtin_amdgcn_rcpf(1.0f + __builtin_amdgcn_exp2f(-1.4426950408889634f * v)); }
; __device__ __forceinline__ float bf_hi(unsigned w) { return __uint_as_float(w & 0xffff0000u); }
; __device__ __forceinline__ unsigned cvt_pk_bf16(float lo, float hi) { f32x2_t v = {lo, hi}; bf16x2_t b = __builtin_convertvector(v, bf16x2_t); return __builtin_bit_cast(unsigned, b); }
;     __device__ __forceinline__ void operator()(const f32x4 (&acc)[2][2][4][2], const Unit& u, int wr, int wc, int fr, int fq) const {
;     ...
;                 for (int m = 0; m < 4; ++m) { const unsigned rl = rl0 + (unsigned)(ai * HALF + m * 16);
;                     const u32x4 yg = ygv[m], sg = sgv[m];
;                     const f32x4 v0 = acc[ai][bj][m][0], v1 = acc[ai][bj][m][1];
;                     u32x4 w;
;                     w.x = cvt_pk_bf16(bf_lo(yg.x) * sigm(v0[0]) * silu_f(bf_lo(sg.x)), bf_hi(yg.x) * sigm(v0[1]) * silu_f(bf_hi(sg.x)));
;                     w.y = cvt_pk_bf16(bf_lo(yg.y) * sigm(v0[2]) * silu_f(bf_lo(sg.y)), bf_hi(yg.y) * sigm(v0[3]) * silu_f(bf_hi(sg.y)));
;                     w.z = cvt_pk_bf16(bf_lo(yg.z) * sigm(v1[0]) * silu_f(bf_lo(sg.z)), bf_hi(yg.z) * sigm(v1[1]) * silu_f(bf_hi(sg.z)));
;                     w.w = cvt_pk_bf16(bf_lo(yg.w) * sigm(v1[2]) * silu_f(bf_lo(sg.w)), bf_hi(yg.w) * sigm(v1[3]) * silu_f(bf_hi(sg.w)));
;                     *(u32x4*)(yb + (rl * 1024u + col) * 2u) = w; }
	v_rcp_f32_e32 v120, v119
	v_mul_f32_e32 v119, 0xbfb8aa3b, v121
	v_exp_f32_e32 v119, v119
	v_add_f32_e32 v72, 1.0, v72
	v_add_f32_e32 v73, 1.0, v73
	v_rcp_f32_e32 v72, v72
	v_add_f32_e32 v119, 1.0, v119
	v_rcp_f32_e32 v121, v119
	v_mul_f32_e32 v119, 0xbfb8aa3b, v126
	v_exp_f32_e32 v119, v119
	v_rcp_f32_e32 v73, v73
	v_pk_mul_f32 v[120:121], v[120:121], v[130:131]
	v_mul_f32_e32 v68, 0xbfb8aa3b, v68
	v_add_f32_e32 v119, 1.0, v119
	v_rcp_f32_e32 v122, v119
	v_mul_f32_e32 v119, 0xbfb8aa3b, v127
	v_exp_f32_e32 v119, v119
	v_mul_f32_e32 v69, 0xbfb8aa3b, v69
	v_exp_f32_e32 v68, v68
	v_exp_f32_e32 v69, v69
	v_add_f32_e32 v119, 1.0, v119
	v_rcp_f32_e32 v123, v119
	v_add_f32_e32 v68, 1.0, v68
	v_add_f32_e32 v69, 1.0, v69
	v_rcp_f32_e32 v68, v68
	v_pk_mul_f32 v[122:123], v[122:123], v[126:127]
	v_lshlrev_b32_e32 v126, 16, v124
	v_pk_mul_f32 v[120:121], v[120:121], v[122:123]
	v_and_b32_e32 v127, 0xffff0000, v124
	v_cvt_pk_bf16_f32 v119, v120, v121
	v_lshlrev_b32_e32 v120, 16, v128
	v_and_b32_e32 v121, 0xffff0000, v128
	v_mul_f32_e32 v122, 0xbfb8aa3b, v120
	v_mul_f32_e32 v123, 0xbfb8aa3b, v121
	v_exp_f32_e32 v122, v122
	v_exp_f32_e32 v123, v123
	v_pk_mul_f32 v[114:115], v[114:115], v[126:127]
	v_lshlrev_b32_e32 v124, 16, v125
	v_add_f32_e32 v122, 1.0, v122
	v_add_f32_e32 v123, 1.0, v123
	v_rcp_f32_e32 v122, v122
	v_rcp_f32_e32 v123, v123
	v_and_b32_e32 v125, 0xffff0000, v125
	v_rcp_f32_e32 v69, v69
	v_mul_f32_e32 v60, 0xbfb8aa3b, v60
	v_pk_mul_f32 v[120:121], v[122:123], v[120:121]
	v_mul_f32_e32 v61, 0xbfb8aa3b, v61
	v_pk_mul_f32 v[114:115], v[114:115], v[120:121]
	v_exp_f32_e32 v60, v60
	v_cvt_pk_bf16_f32 v120, v114, v115
	v_mul_f32_e32 v114, 0xbfb8aa3b, v116
	v_lshlrev_b32_e32 v116, 16, v129
	v_mul_f32_e32 v121, 0xbfb8aa3b, v116
	v_exp_f32_e32 v121, v121
	v_mul_f32_e32 v115, 0xbfb8aa3b, v117
	v_and_b32_e32 v117, 0xffff0000, v129
	v_exp_f32_e32 v114, v114
	v_add_f32_e32 v121, 1.0, v121
	v_rcp_f32_e32 v122, v121
	v_mul_f32_e32 v121, 0xbfb8aa3b, v117
	v_exp_f32_e32 v115, v115
	v_exp_f32_e32 v121, v121
	v_add_f32_e32 v114, 1.0, v114
	v_rcp_f32_e32 v114, v114
	v_add_f32_e32 v115, 1.0, v115
	v_add_f32_e32 v121, 1.0, v121
	v_rcp_f32_e32 v115, v115
	v_rcp_f32_e32 v123, v121
	v_exp_f32_e32 v61, v61
	v_add_f32_e32 v60, 1.0, v60
	v_pk_mul_f32 v[114:115], v[114:115], v[124:125]
	v_pk_mul_f32 v[116:117], v[122:123], v[116:117]
	v_add_f32_e32 v61, 1.0, v61
	v_pk_mul_f32 v[114:115], v[114:115], v[116:117]
	v_rcp_f32_e32 v60, v60
	v_cvt_pk_bf16_f32 v121, v114, v115
	v_add_u32_e32 v114, 0x10000, v146
	global_store_dwordx4 v114, v[118:121], s[60:61] offset:1536 nt sc1
	v_lshlrev_b32_e32 v114, 16, v110
	v_and_b32_e32 v115, 0xffff0000, v110
	v_mul_f32_e32 v110, 0xbfb8aa3b, v114
	v_lshlrev_b32_e32 v118, 16, v106
	v_and_b32_e32 v119, 0xffff0000, v106
	v_mul_f32_e32 v106, 0xbfb8aa3b, v115
	v_exp_f32_e32 v110, v110
	v_exp_f32_e32 v106, v106
	v_pk_mul_f32 v[102:103], v[102:103], v[118:119]
	v_rcp_f32_e32 v61, v61
	v_add_f32_e32 v110, 1.0, v110
	v_add_f32_e32 v106, 1.0, v106
	v_rcp_f32_e32 v116, v110
	v_rcp_f32_e32 v117, v106
	v_lshlrev_b32_e32 v110, 16, v111
	v_and_b32_e32 v111, 0xffff0000, v111
	v_mul_f32_e32 v64, 0xbfb8aa3b, v64
	v_pk_mul_f32 v[114:115], v[116:117], v[114:115]
	v_mul_f32_e32 v65, 0xbfb8aa3b, v65
	v_pk_mul_f32 v[102:103], v[102:103], v[114:115]
	v_lshlrev_b32_e32 v114, 16, v107
	v_cvt_pk_bf16_f32 v102, v102, v103
	v_mul_f32_e32 v103, 0xbfb8aa3b, v104
	v_exp_f32_e32 v103, v103
	v_and_b32_e32 v115, 0xffff0000, v107
	v_exp_f32_e32 v64, v64
	v_exp_f32_e32 v65, v65
	v_add_f32_e32 v103, 1.0, v103
	v_rcp_f32_e32 v104, v103
	v_mul_f32_e32 v103, 0xbfb8aa3b, v105
	v_exp_f32_e32 v103, v103
	v_add_f32_e32 v64, 1.0, v64
	v_add_f32_e32 v65, 1.0, v65
	v_rcp_f32_e32 v64, v64
	v_add_f32_e32 v103, 1.0, v103
	v_rcp_f32_e32 v105, v103
	v_mul_f32_e32 v103, 0xbfb8aa3b, v110
	v_exp_f32_e32 v103, v103
	v_rcp_f32_e32 v65, v65
	v_pk_mul_f32 v[104:105], v[104:105], v[114:115]
	v_mul_f32_e32 v56, 0xbfb8aa3b, v56
	v_add_f32_e32 v103, 1.0, v103
	v_rcp_f32_e32 v106, v103
	v_mul_f32_e32 v103, 0xbfb8aa3b, v111
	v_exp_f32_e32 v103, v103
	v_mul_f32_e32 v57, 0xbfb8aa3b, v57
	v_exp_f32_e32 v56, v56
	v_exp_f32_e32 v57, v57
	v_add_f32_e32 v103, 1.0, v103
	v_rcp_f32_e32 v107, v103
	v_add_f32_e32 v56, 1.0, v56
	v_add_f32_e32 v57, 1.0, v57
	v_rcp_f32_e32 v56, v56
	v_pk_mul_f32 v[106:107], v[106:107], v[110:111]
	v_lshlrev_b32_e32 v110, 16, v108
	v_pk_mul_f32 v[104:105], v[104:105], v[106:107]
	v_and_b32_e32 v111, 0xffff0000, v108
	v_cvt_pk_bf16_f32 v103, v104, v105
	v_lshlrev_b32_e32 v104, 16, v112
	v_and_b32_e32 v105, 0xffff0000, v112
	v_mul_f32_e32 v106, 0xbfb8aa3b, v104
	v_mul_f32_e32 v107, 0xbfb8aa3b, v105
	v_exp_f32_e32 v106, v106
	v_exp_f32_e32 v107, v107
	v_pk_mul_f32 v[98:99], v[98:99], v[110:111]
	v_lshlrev_b32_e32 v108, 16, v109
	v_add_f32_e32 v106, 1.0, v106
	v_add_f32_e32 v107, 1.0, v107
	v_rcp_f32_e32 v106, v106
	v_rcp_f32_e32 v107, v107
	v_and_b32_e32 v109, 0xffff0000, v109
	v_rcp_f32_e32 v57, v57
	v_mul_f32_e32 v52, 0xbfb8aa3b, v52
	v_pk_mul_f32 v[104:105], v[106:107], v[104:105]
	v_mul_f32_e32 v53, 0xbfb8aa3b, v53
	v_pk_mul_f32 v[98:99], v[98:99], v[104:105]
	v_exp_f32_e32 v52, v52
	v_cvt_pk_bf16_f32 v104, v98, v99
	v_mul_f32_e32 v98, 0xbfb8aa3b, v100
	v_lshlrev_b32_e32 v100, 16, v113
	v_mul_f32_e32 v105, 0xbfb8aa3b, v100
	v_exp_f32_e32 v105, v105
	v_mul_f32_e32 v99, 0xbfb8aa3b, v101
	v_and_b32_e32 v101, 0xffff0000, v113
	v_exp_f32_e32 v98, v98
	v_add_f32_e32 v105, 1.0, v105
	v_rcp_f32_e32 v106, v105
	v_mul_f32_e32 v105, 0xbfb8aa3b, v101
	v_exp_f32_e32 v99, v99
	v_exp_f32_e32 v105, v105
	v_add_f32_e32 v98, 1.0, v98
	v_rcp_f32_e32 v98, v98
	v_add_f32_e32 v99, 1.0, v99
; __device__ __forceinline__ float sigm(float v) { return __builtin_amdgcn_rcpf(1.0f + __builtin_amdgcn_exp2f(-LOG2E * v)); }
; __device__ __forceinline__ float bf_lo(unsigned w) { return __uint_as_float(w << 16); }
; __device__ __forceinline__ float silu_f(float v) { return v * __builtin_amdgcn_rcpf(1.0f + __builtin_amdgcn_exp2f(-1.4426950408889634f * v)); }
; __device__ __forceinline__ float bf_hi(unsigned w) { return __uint_as_float(w & 0xffff0000u); }
; __device__ __forceinline__ unsigned cvt_pk_bf16(float lo, float hi) { f32x2_t v = {lo, hi}; bf16x2_t b = __builtin_convertvector(v, bf16x2_t); return __builtin_bit_cast(unsigned, b); }
;     __device__ __forceinline__ void operator()(const f32x4 (&acc)[2][2][4][2], const Unit& u, int wr, int wc, int fr, int fq) const {
;     ...
;         for (int bj = 0; bj < 2; ++bj) { const unsigned col = col0 + bj * HALF;
; #pragma unroll
;             for (int ai = 0; ai < 2; ++ai) {
;                 u32x4 ygv[4], sgv[4];
; #pragma unroll
;                 for (int m = 0; m < 4; ++m) { const unsigned rl = rl0 + (unsigned)(ai * HALF + m * 16);
;                     ygv[m] = *(const u32x4*)(ygb + (rl * 256u + col) * 2u); sgv[m] = *(const u32x4*)(sgb + (rl * 512u + col) * 2u); }
; #pragma unroll
;                 for (int m = 0; m < 4; ++m) { const unsigned rl = rl0 + (unsigned)(ai * HALF + m * 16);
;                     const u32x4 yg = ygv[m], sg = sgv[m];
;                     const f32x4 v0 = acc[ai][bj][m][0], v1 = acc[ai][bj][m][1];
;                     u32x4 w;
;                     w.x = cvt_pk_bf16(bf_lo(yg.x) * sigm(v0[0]) * silu_f(bf_lo(sg.x)), bf_hi(yg.x) * sigm(v0[1]) * silu_f(bf_hi(sg.x)));
;                     w.y = cvt_pk_bf16(bf_lo(yg.y) * sigm(v0[2]) * silu_f(bf_lo(sg.y)), bf_hi(yg.y) * sigm(v0[3]) * silu_f(bf_hi(sg.y)));
;                     w.z = cvt_pk_bf16(bf_lo(yg.z) * sigm(v1[0]) * silu_f(bf_lo(sg.z)), bf_hi(yg.z) * sigm(v1[1]) * silu_f(bf_hi(sg.z)));
;                     w.w = cvt_pk_bf16(bf_lo(yg.w) * sigm(v1[2]) * silu_f(bf_lo(sg.w)), bf_hi(yg.w) * sigm(v1[3]) * silu_f(bf_hi(sg.w)));
;                     *(u32x4*)(yb + (rl * 1024u + col) * 2u) = w; }
	v_add_f32_e32 v105, 1.0, v105
	v_rcp_f32_e32 v99, v99
	v_rcp_f32_e32 v107, v105
	v_exp_f32_e32 v53, v53
	v_add_f32_e32 v52, 1.0, v52
	v_pk_mul_f32 v[98:99], v[98:99], v[108:109]
	v_pk_mul_f32 v[100:101], v[106:107], v[100:101]
	v_add_f32_e32 v53, 1.0, v53
	v_pk_mul_f32 v[98:99], v[98:99], v[100:101]
	v_rcp_f32_e32 v52, v52
	v_cvt_pk_bf16_f32 v105, v98, v99
	v_add_u32_e32 v98, 0x18000, v146
	global_store_dwordx4 v98, v[102:105], s[60:61] offset:1536 nt sc1
	v_rcp_f32_e32 v53, v53
	v_lshlrev_b32_e32 v98, 9, v174
	v_add_u32_e32 v99, 0x10000, v98
	v_add_u32_e32 v100, v99, v176
	v_add_u32_e32 v99, v100, v99
	global_load_dwordx4 v[122:125], v100, s[62:63] nt
	global_load_dwordx4 v[126:129], v99, s[64:65] nt
	v_add_u32_e32 v99, 0x12000, v98
	v_add_u32_e32 v100, v99, v176
	v_add_u32_e32 v99, v100, v99
	global_load_dwordx4 v[114:117], v100, s[62:63] nt
	global_load_dwordx4 v[118:121], v99, s[64:65] nt
	v_add_u32_e32 v99, 0x14000, v98
	v_add_u32_e32 v102, 0x16000, v98
	v_add_u32_e32 v100, v99, v176
	v_add_u32_e32 v103, v102, v176
	v_add_u32_e32 v99, v100, v99
	v_add_u32_e32 v102, v103, v102
	global_load_dwordx4 v[106:109], v100, s[62:63] nt
	global_load_dwordx4 v[110:113], v99, s[64:65] nt
	v_mul_f32_e32 v48, 0xbfb8aa3b, v48
	global_load_dwordx4 v[98:101], v103, s[62:63] nt
	v_mul_f32_e32 v49, 0xbfb8aa3b, v49
	global_load_dwordx4 v[102:105], v102, s[64:65] nt
	v_exp_f32_e32 v48, v48
	v_exp_f32_e32 v49, v49
	v_mul_f32_e32 v44, 0xbfb8aa3b, v44
	v_mul_f32_e32 v45, 0xbfb8aa3b, v45
	v_add_f32_e32 v48, 1.0, v48
	v_add_f32_e32 v49, 1.0, v49
	v_rcp_f32_e32 v48, v48
	v_rcp_f32_e32 v49, v49
	v_exp_f32_e32 v44, v44
	v_exp_f32_e32 v45, v45
	v_mul_f32_e32 v40, 0xbfb8aa3b, v40
	v_mul_f32_e32 v41, 0xbfb8aa3b, v41
	v_add_f32_e32 v44, 1.0, v44
	v_add_f32_e32 v45, 1.0, v45
	v_rcp_f32_e32 v44, v44
	v_rcp_f32_e32 v45, v45
	v_exp_f32_e32 v40, v40
	v_exp_f32_e32 v41, v41
	v_mul_f32_e32 v36, 0xbfb8aa3b, v36
	v_mul_f32_e32 v37, 0xbfb8aa3b, v37
	v_add_f32_e32 v40, 1.0, v40
	v_add_f32_e32 v41, 1.0, v41
	v_rcp_f32_e32 v40, v40
	v_rcp_f32_e32 v41, v41
	v_exp_f32_e32 v36, v36
	v_exp_f32_e32 v37, v37
	v_mul_f32_e32 v32, 0xbfb8aa3b, v32
	v_mul_f32_e32 v33, 0xbfb8aa3b, v33
	v_add_f32_e32 v36, 1.0, v36
	v_add_f32_e32 v37, 1.0, v37
	v_rcp_f32_e32 v36, v36
	v_rcp_f32_e32 v37, v37
	v_exp_f32_e32 v32, v32
	v_exp_f32_e32 v33, v33
	v_mul_f32_e32 v28, 0xbfb8aa3b, v28
	v_mul_f32_e32 v29, 0xbfb8aa3b, v29
	v_add_f32_e32 v32, 1.0, v32
	v_add_f32_e32 v33, 1.0, v33
	v_rcp_f32_e32 v32, v32
	v_rcp_f32_e32 v33, v33
	v_exp_f32_e32 v28, v28
	v_exp_f32_e32 v29, v29
	v_mul_f32_e32 v24, 0xbfb8aa3b, v24
	v_mul_f32_e32 v25, 0xbfb8aa3b, v25
	v_add_f32_e32 v28, 1.0, v28
	v_add_f32_e32 v29, 1.0, v29
	v_rcp_f32_e32 v28, v28
	v_rcp_f32_e32 v29, v29
	v_exp_f32_e32 v24, v24
	v_exp_f32_e32 v25, v25
	v_mul_f32_e32 v20, 0xbfb8aa3b, v20
	v_mul_f32_e32 v21, 0xbfb8aa3b, v21
	v_add_f32_e32 v24, 1.0, v24
	v_add_f32_e32 v25, 1.0, v25
	v_rcp_f32_e32 v24, v24
	v_rcp_f32_e32 v25, v25
	v_exp_f32_e32 v20, v20
	v_exp_f32_e32 v21, v21
	v_mul_f32_e32 v16, 0xbfb8aa3b, v16
	v_mul_f32_e32 v17, 0xbfb8aa3b, v17
	v_add_f32_e32 v20, 1.0, v20
	s_waitcnt vmcnt(7)
	v_lshlrev_b32_e32 v134, 16, v122
	s_waitcnt vmcnt(6)
	v_lshlrev_b32_e32 v130, 16, v126
	v_and_b32_e32 v131, 0xffff0000, v126
	v_mul_f32_e32 v126, 0xbfb8aa3b, v130
	v_and_b32_e32 v135, 0xffff0000, v122
	v_mul_f32_e32 v122, 0xbfb8aa3b, v131
	v_exp_f32_e32 v126, v126
	v_exp_f32_e32 v122, v122
	v_pk_mul_f32 v[92:93], v[92:93], v[134:135]
	v_add_f32_e32 v21, 1.0, v21
	v_add_f32_e32 v126, 1.0, v126
	v_add_f32_e32 v122, 1.0, v122
	v_rcp_f32_e32 v132, v126
	v_rcp_f32_e32 v133, v122
	v_lshlrev_b32_e32 v126, 16, v127
	v_and_b32_e32 v127, 0xffff0000, v127
	v_rcp_f32_e32 v20, v20
	v_pk_mul_f32 v[130:131], v[132:133], v[130:131]
	v_rcp_f32_e32 v21, v21
	v_pk_mul_f32 v[92:93], v[92:93], v[130:131]
	v_lshlrev_b32_e32 v130, 16, v123
	v_cvt_pk_bf16_f32 v92, v92, v93
	v_mul_f32_e32 v93, 0xbfb8aa3b, v94
	v_exp_f32_e32 v93, v93
	v_and_b32_e32 v131, 0xffff0000, v123
	v_exp_f32_e32 v16, v16
	v_exp_f32_e32 v17, v17
	v_add_f32_e32 v93, 1.0, v93
	v_rcp_f32_e32 v94, v93
	v_mul_f32_e32 v93, 0xbfb8aa3b, v95
	v_exp_f32_e32 v93, v93
	v_add_f32_e32 v16, 1.0, v16
	v_add_f32_e32 v17, 1.0, v17
	v_rcp_f32_e32 v16, v16
	v_add_f32_e32 v93, 1.0, v93
	v_rcp_f32_e32 v95, v93
	v_mul_f32_e32 v93, 0xbfb8aa3b, v126
	v_exp_f32_e32 v93, v93
	v_rcp_f32_e32 v17, v17
	v_pk_mul_f32 v[94:95], v[94:95], v[130:131]
	v_mul_f32_e32 v12, 0xbfb8aa3b, v12
	v_add_f32_e32 v93, 1.0, v93
	v_rcp_f32_e32 v122, v93
	v_mul_f32_e32 v93, 0xbfb8aa3b, v127
	v_exp_f32_e32 v93, v93
	v_mul_f32_e32 v13, 0xbfb8aa3b, v13
	v_exp_f32_e32 v12, v12
	v_exp_f32_e32 v13, v13
	v_add_f32_e32 v93, 1.0, v93
	v_rcp_f32_e32 v123, v93
	v_add_f32_e32 v12, 1.0, v12
	v_add_f32_e32 v13, 1.0, v13
	v_rcp_f32_e32 v12, v12
	v_pk_mul_f32 v[122:123], v[122:123], v[126:127]
	v_lshlrev_b32_e32 v126, 16, v124
	v_pk_mul_f32 v[94:95], v[94:95], v[122:123]
	v_and_b32_e32 v127, 0xffff0000, v124
	v_cvt_pk_bf16_f32 v93, v94, v95
	v_lshlrev_b32_e32 v94, 16, v128
	v_and_b32_e32 v95, 0xffff0000, v128
	v_mul_f32_e32 v122, 0xbfb8aa3b, v94
	v_mul_f32_e32 v123, 0xbfb8aa3b, v95
	v_exp_f32_e32 v122, v122
	v_exp_f32_e32 v123, v123
	v_pk_mul_f32 v[88:89], v[88:89], v[126:127]
	v_lshlrev_b32_e32 v124, 16, v125
	v_add_f32_e32 v122, 1.0, v122
	v_add_f32_e32 v123, 1.0, v123
	v_rcp_f32_e32 v122, v122
	v_rcp_f32_e32 v123, v123
	v_and_b32_e32 v125, 0xffff0000, v125
	v_rcp_f32_e32 v13, v13
	v_mul_f32_e32 v8, 0xbfb8aa3b, v8
	v_pk_mul_f32 v[94:95], v[122:123], v[94:95]
	v_mul_f32_e32 v9, 0xbfb8aa3b, v9
	v_pk_mul_f32 v[88:89], v[88:89], v[94:95]
	v_exp_f32_e32 v8, v8
	v_cvt_pk_bf16_f32 v94, v88, v89
	v_mul_f32_e32 v88, 0xbfb8aa3b, v90
	v_lshlrev_b32_e32 v90, 16, v129
	v_mul_f32_e32 v95, 0xbfb8aa3b, v90
	v_exp_f32_e32 v95, v95
	v_mul_f32_e32 v89, 0xbfb8aa3b, v91
	v_and_b32_e32 v91, 0xffff0000, v129
	v_exp_f32_e32 v88, v88
	v_add_f32_e32 v95, 1.0, v95
	v_rcp_f32_e32 v122, v95
	v_mul_f32_e32 v95, 0xbfb8aa3b, v91
	v_exp_f32_e32 v89, v89
	v_exp_f32_e32 v95, v95
	v_add_f32_e32 v88, 1.0, v88
	v_rcp_f32_e32 v88, v88
	v_add_f32_e32 v89, 1.0, v89
	v_add_f32_e32 v95, 1.0, v95
	v_rcp_f32_e32 v89, v89
	v_rcp_f32_e32 v123, v95
	v_exp_f32_e32 v9, v9
	v_add_f32_e32 v8, 1.0, v8
	v_pk_mul_f32 v[88:89], v[88:89], v[124:125]
	v_pk_mul_f32 v[90:91], v[122:123], v[90:91]
	v_add_f32_e32 v9, 1.0, v9
	v_pk_mul_f32 v[88:89], v[88:89], v[90:91]
	s_waitcnt vmcnt(4)
; __device__ __forceinline__ float sigm(float v) { return __builtin_amdgcn_rcpf(1.0f + __builtin_amdgcn_exp2f(-LOG2E * v)); }
; __device__ __forceinline__ float bf_lo(unsigned w) { return __uint_as_float(w << 16); }
; __device__ __forceinline__ float silu_f(float v) { return v * __builtin_amdgcn_rcpf(1.0f + __builtin_amdgcn_exp2f(-1.4426950408889634f * v)); }
; __device__ __forceinline__ float bf_hi(unsigned w) { return __uint_as_float(w & 0xffff0000u); }
; __device__ __forceinline__ unsigned cvt_pk_bf16(float lo, float hi) { f32x2_t v = {lo, hi}; bf16x2_t b = __builtin_convertvector(v, bf16x2_t); return __builtin_bit_cast(unsigned, b); }
;     __device__ __forceinline__ void operator()(const f32x4 (&acc)[2][2][4][2], const Unit& u, int wr, int wc, int fr, int fq) const {
;     ...
;         for (int bj = 0; bj < 2; ++bj) { const unsigned col = col0 + bj * HALF;
; #pragma unroll
;             for (int ai = 0; ai < 2; ++ai) {
;                 u32x4 ygv[4], sgv[4];
; #pragma unroll
;                 for (int m = 0; m < 4; ++m) { const unsigned rl = rl0 + (unsigned)(ai * HALF + m * 16);
;                     ygv[m] = *(const u32x4*)(ygb + (rl * 256u + col) * 2u); sgv[m] = *(const u32x4*)(sgb + (rl * 512u + col) * 2u); }
; #pragma unroll
;                 for (int m = 0; m < 4; ++m) { const unsigned rl = rl0 + (unsigned)(ai * HALF + m * 16);
;                     const u32x4 yg = ygv[m], sg = sgv[m];
;                     const f32x4 v0 = acc[ai][bj][m][0], v1 = acc[ai][bj][m][1];
;                     u32x4 w;
;                     w.x = cvt_pk_bf16(bf_lo(yg.x) * sigm(v0[0]) * silu_f(bf_lo(sg.x)), bf_hi(yg.x) * sigm(v0[1]) * silu_f(bf_hi(sg.x)));
;                     w.y = cvt_pk_bf16(bf_lo(yg.y) * sigm(v0[2]) * silu_f(bf_lo(sg.y)), bf_hi(yg.y) * sigm(v0[3]) * silu_f(bf_hi(sg.y)));
;                     w.z = cvt_pk_bf16(bf_lo(yg.z) * sigm(v1[0]) * silu_f(bf_lo(sg.z)), bf_hi(yg.z) * sigm(v1[1]) * silu_f(bf_hi(sg.z)));
;                     w.w = cvt_pk_bf16(bf_lo(yg.w) * sigm(v1[2]) * silu_f(bf_lo(sg.w)), bf_hi(yg.w) * sigm(v1[3]) * silu_f(bf_hi(sg.w)));
;                     *(u32x4*)(yb + (rl * 1024u + col) * 2u) = w; }
	v_lshlrev_b32_e32 v90, 16, v118
	v_cvt_pk_bf16_f32 v95, v88, v89
	v_lshl_add_u32 v88, v174, 11, v176
	v_add_u32_e32 v89, 0x40000, v88
	global_store_dwordx4 v89, v[92:95], s[60:61] offset:1536 nt sc1
	v_mul_f32_e32 v89, 0xbfb8aa3b, v90
	v_exp_f32_e32 v89, v89
	v_and_b32_e32 v91, 0xffff0000, v118
	v_lshlrev_b32_e32 v94, 16, v114
	v_and_b32_e32 v95, 0xffff0000, v114
	v_add_f32_e32 v89, 1.0, v89
	v_rcp_f32_e32 v92, v89
	v_mul_f32_e32 v89, 0xbfb8aa3b, v91
	v_exp_f32_e32 v89, v89
	v_pk_mul_f32 v[84:85], v[84:85], v[94:95]
	v_lshlrev_b32_e32 v94, 16, v115
	v_and_b32_e32 v95, 0xffff0000, v115
	v_add_f32_e32 v89, 1.0, v89
	v_rcp_f32_e32 v93, v89
	v_rcp_f32_e32 v8, v8
	v_rcp_f32_e32 v9, v9
	v_mul_f32_e32 v4, 0xbfb8aa3b, v4
	v_pk_mul_f32 v[90:91], v[92:93], v[90:91]
	v_mul_f32_e32 v5, 0xbfb8aa3b, v5
	v_pk_mul_f32 v[84:85], v[84:85], v[90:91]
	v_lshlrev_b32_e32 v90, 16, v119
	v_cvt_pk_bf16_f32 v84, v84, v85
	v_mul_f32_e32 v85, 0xbfb8aa3b, v86
	v_exp_f32_e32 v85, v85
	v_and_b32_e32 v91, 0xffff0000, v119
	v_exp_f32_e32 v4, v4
	v_exp_f32_e32 v5, v5
	v_add_f32_e32 v85, 1.0, v85
	v_rcp_f32_e32 v86, v85
	v_mul_f32_e32 v85, 0xbfb8aa3b, v87
	v_exp_f32_e32 v85, v85
	v_add_f32_e32 v4, 1.0, v4
	v_add_f32_e32 v5, 1.0, v5
	v_rcp_f32_e32 v4, v4
	v_add_f32_e32 v85, 1.0, v85
	v_rcp_f32_e32 v87, v85
	v_mul_f32_e32 v85, 0xbfb8aa3b, v90
	v_exp_f32_e32 v85, v85
	v_rcp_f32_e32 v5, v5
	v_pk_mul_f32 v[86:87], v[86:87], v[94:95]
	v_mul_f32_e32 v0, 0xbfb8aa3b, v0
	v_add_f32_e32 v85, 1.0, v85
	v_rcp_f32_e32 v92, v85
	v_mul_f32_e32 v85, 0xbfb8aa3b, v91
	v_exp_f32_e32 v85, v85
	v_mul_f32_e32 v1, 0xbfb8aa3b, v1
	v_exp_f32_e32 v0, v0
	v_exp_f32_e32 v1, v1
	v_add_f32_e32 v85, 1.0, v85
	v_rcp_f32_e32 v93, v85
	v_add_f32_e32 v0, 1.0, v0
	v_add_f32_e32 v1, 1.0, v1
	v_rcp_f32_e32 v0, v0
	v_pk_mul_f32 v[90:91], v[92:93], v[90:91]
	v_lshlrev_b32_e32 v92, 16, v116
	v_pk_mul_f32 v[86:87], v[86:87], v[90:91]
	v_and_b32_e32 v93, 0xffff0000, v116
	v_cvt_pk_bf16_f32 v85, v86, v87
	v_lshlrev_b32_e32 v86, 16, v120
	v_mul_f32_e32 v89, 0xbfb8aa3b, v86
	v_exp_f32_e32 v89, v89
	v_and_b32_e32 v87, 0xffff0000, v120
	v_pk_mul_f32 v[80:81], v[80:81], v[92:93]
	v_lshlrev_b32_e32 v92, 16, v117
	v_add_f32_e32 v89, 1.0, v89
	v_rcp_f32_e32 v90, v89
	v_mul_f32_e32 v89, 0xbfb8aa3b, v87
	v_exp_f32_e32 v89, v89
	v_and_b32_e32 v93, 0xffff0000, v117
	v_rcp_f32_e32 v1, v1
	s_and_b64 vcc, exec, s[38:39]
	v_add_f32_e32 v89, 1.0, v89
	v_rcp_f32_e32 v91, v89
	s_nop 0
	v_pk_mul_f32 v[86:87], v[90:91], v[86:87]
	s_nop 0
	v_pk_mul_f32 v[80:81], v[80:81], v[86:87]
	s_nop 0
	v_cvt_pk_bf16_f32 v86, v80, v81
	v_mul_f32_e32 v80, 0xbfb8aa3b, v82
	v_lshlrev_b32_e32 v82, 16, v121
	v_mul_f32_e32 v87, 0xbfb8aa3b, v82
	v_exp_f32_e32 v87, v87
	v_mul_f32_e32 v81, 0xbfb8aa3b, v83
	v_and_b32_e32 v83, 0xffff0000, v121
	v_exp_f32_e32 v80, v80
	v_add_f32_e32 v87, 1.0, v87
	v_rcp_f32_e32 v90, v87
	v_mul_f32_e32 v87, 0xbfb8aa3b, v83
	v_exp_f32_e32 v81, v81
	v_exp_f32_e32 v87, v87
	v_add_f32_e32 v80, 1.0, v80
	v_rcp_f32_e32 v80, v80
	v_add_f32_e32 v81, 1.0, v81
	v_add_f32_e32 v87, 1.0, v87
	v_rcp_f32_e32 v81, v81
	v_rcp_f32_e32 v91, v87
	v_pk_mul_f32 v[80:81], v[80:81], v[92:93]
	v_pk_mul_f32 v[82:83], v[90:91], v[82:83]
	s_nop 0
	v_pk_mul_f32 v[80:81], v[80:81], v[82:83]
	s_nop 0
	v_cvt_pk_bf16_f32 v87, v80, v81
	v_add_u32_e32 v80, 0x48000, v88
	global_store_dwordx4 v80, v[84:87], s[60:61] offset:1536 nt sc1
	s_waitcnt vmcnt(4)
	v_lshlrev_b32_e32 v80, 16, v110
	v_and_b32_e32 v81, 0xffff0000, v110
	v_mul_f32_e32 v82, 0xbfb8aa3b, v80
	v_mul_f32_e32 v83, 0xbfb8aa3b, v81
	v_exp_f32_e32 v82, v82
	v_exp_f32_e32 v83, v83
	v_lshlrev_b32_e32 v84, 16, v106
	v_and_b32_e32 v85, 0xffff0000, v106
	v_add_f32_e32 v82, 1.0, v82
	v_add_f32_e32 v83, 1.0, v83
	v_rcp_f32_e32 v82, v82
	v_rcp_f32_e32 v83, v83
	v_pk_mul_f32 v[76:77], v[76:77], v[84:85]
	v_lshlrev_b32_e32 v84, 16, v107
	v_and_b32_e32 v85, 0xffff0000, v107
	v_pk_mul_f32 v[80:81], v[82:83], v[80:81]
	s_nop 0
	v_pk_mul_f32 v[76:77], v[76:77], v[80:81]
	v_lshlrev_b32_e32 v80, 16, v111
	v_cvt_pk_bf16_f32 v76, v76, v77
	v_mul_f32_e32 v77, 0xbfb8aa3b, v78
	v_exp_f32_e32 v77, v77
	v_and_b32_e32 v81, 0xffff0000, v111
	v_add_f32_e32 v77, 1.0, v77
	v_rcp_f32_e32 v78, v77
	v_mul_f32_e32 v77, 0xbfb8aa3b, v79
	v_exp_f32_e32 v77, v77
	s_nop 0
	v_add_f32_e32 v77, 1.0, v77
	v_rcp_f32_e32 v79, v77
	v_mul_f32_e32 v77, 0xbfb8aa3b, v80
	v_exp_f32_e32 v77, v77
	v_pk_mul_f32 v[78:79], v[78:79], v[84:85]
	v_add_f32_e32 v77, 1.0, v77
	v_rcp_f32_e32 v82, v77
	v_mul_f32_e32 v77, 0xbfb8aa3b, v81
	v_exp_f32_e32 v77, v77
	s_nop 0
	v_add_f32_e32 v77, 1.0, v77
	v_rcp_f32_e32 v83, v77
	s_nop 0
	v_pk_mul_f32 v[80:81], v[82:83], v[80:81]
	s_nop 0
	v_pk_mul_f32 v[78:79], v[78:79], v[80:81]
	v_lshlrev_b32_e32 v82, 16, v108
	v_cvt_pk_bf16_f32 v77, v78, v79
	v_lshlrev_b32_e32 v78, 16, v112
	v_and_b32_e32 v79, 0xffff0000, v112
	v_mul_f32_e32 v80, 0xbfb8aa3b, v78
	v_mul_f32_e32 v81, 0xbfb8aa3b, v79
	v_exp_f32_e32 v80, v80
	v_exp_f32_e32 v81, v81
	v_and_b32_e32 v83, 0xffff0000, v108
	v_pk_mul_f32 v[72:73], v[72:73], v[82:83]
	v_add_f32_e32 v80, 1.0, v80
	v_add_f32_e32 v81, 1.0, v81
	v_rcp_f32_e32 v80, v80
	v_rcp_f32_e32 v81, v81
	v_lshlrev_b32_e32 v82, 16, v109
	v_and_b32_e32 v83, 0xffff0000, v109
	v_pk_mul_f32 v[78:79], v[80:81], v[78:79]
	s_nop 0
	v_pk_mul_f32 v[72:73], v[72:73], v[78:79]
	s_nop 0
	v_cvt_pk_bf16_f32 v78, v72, v73
	v_mul_f32_e32 v72, 0xbfb8aa3b, v74
	v_lshlrev_b32_e32 v74, 16, v113
	v_mul_f32_e32 v79, 0xbfb8aa3b, v74
	v_exp_f32_e32 v79, v79
	v_mul_f32_e32 v73, 0xbfb8aa3b, v75
	v_and_b32_e32 v75, 0xffff0000, v113
	v_exp_f32_e32 v72, v72
	v_add_f32_e32 v79, 1.0, v79
	v_rcp_f32_e32 v80, v79
	v_mul_f32_e32 v79, 0xbfb8aa3b, v75
	v_exp_f32_e32 v73, v73
	v_exp_f32_e32 v79, v79
	v_add_f32_e32 v72, 1.0, v72
	v_rcp_f32_e32 v72, v72
	v_add_f32_e32 v73, 1.0, v73
	v_add_f32_e32 v79, 1.0, v79
	v_rcp_f32_e32 v73, v73
	v_rcp_f32_e32 v81, v79
	v_pk_mul_f32 v[72:73], v[72:73], v[82:83]
	v_pk_mul_f32 v[74:75], v[80:81], v[74:75]
	s_nop 0
	v_pk_mul_f32 v[72:73], v[72:73], v[74:75]
	s_nop 0
	v_cvt_pk_bf16_f32 v79, v72, v73
	v_add_u32_e32 v72, 0x50000, v88
	global_store_dwordx4 v72, v[76:79], s[60:61] offset:1536 nt sc1
	s_waitcnt vmcnt(3)
; __device__ __forceinline__ float sigm(float v) { return __builtin_amdgcn_rcpf(1.0f + __builtin_amdgcn_exp2f(-LOG2E * v)); }
; __device__ __forceinline__ float bf_lo(unsigned w) { return __uint_as_float(w << 16); }
; __device__ __forceinline__ float silu_f(float v) { return v * __builtin_amdgcn_rcpf(1.0f + __builtin_amdgcn_exp2f(-1.4426950408889634f * v)); }
; __device__ __forceinline__ float bf_hi(unsigned w) { return __uint_as_float(w & 0xffff0000u); }
; __device__ __forceinline__ unsigned cvt_pk_bf16(float lo, float hi) { f32x2_t v = {lo, hi}; bf16x2_t b = __builtin_convertvector(v, bf16x2_t); return __builtin_bit_cast(unsigned, b); }
;     __device__ __forceinline__ void operator()(const f32x4 (&acc)[2][2][4][2], const Unit& u, int wr, int wc, int fr, int fq) const {
;     ...
;         for (int bj = 0; bj < 2; ++bj) { const unsigned col = col0 + bj * HALF;
; #pragma unroll
;             for (int ai = 0; ai < 2; ++ai) {
;                 u32x4 ygv[4], sgv[4];
; #pragma unroll
;                 for (int m = 0; m < 4; ++m) { const unsigned rl = rl0 + (unsigned)(ai * HALF + m * 16);
;                     ygv[m] = *(const u32x4*)(ygb + (rl * 256u + col) * 2u); sgv[m] = *(const u32x4*)(sgb + (rl * 512u + col) * 2u); }
; #pragma unroll
;                 for (int m = 0; m < 4; ++m) { const unsigned rl = rl0 + (unsigned)(ai * HALF + m * 16);
;                     const u32x4 yg = ygv[m], sg = sgv[m];
;                     const f32x4 v0 = acc[ai][bj][m][0], v1 = acc[ai][bj][m][1];
;                     u32x4 w;
;                     w.x = cvt_pk_bf16(bf_lo(yg.x) * sigm(v0[0]) * silu_f(bf_lo(sg.x)), bf_hi(yg.x) * sigm(v0[1]) * silu_f(bf_hi(sg.x)));
;                     w.y = cvt_pk_bf16(bf_lo(yg.y) * sigm(v0[2]) * silu_f(bf_lo(sg.y)), bf_hi(yg.y) * sigm(v0[3]) * silu_f(bf_hi(sg.y)));
;                     w.z = cvt_pk_bf16(bf_lo(yg.z) * sigm(v1[0]) * silu_f(bf_lo(sg.z)), bf_hi(yg.z) * sigm(v1[1]) * silu_f(bf_hi(sg.z)));
;                     w.w = cvt_pk_bf16(bf_lo(yg.w) * sigm(v1[2]) * silu_f(bf_lo(sg.w)), bf_hi(yg.w) * sigm(v1[3]) * silu_f(bf_hi(sg.w)));
;                     *(u32x4*)(yb + (rl * 1024u + col) * 2u) = w; }
	v_lshlrev_b32_e32 v72, 16, v102
	v_and_b32_e32 v73, 0xffff0000, v102
	v_mul_f32_e32 v74, 0xbfb8aa3b, v72
	v_mul_f32_e32 v75, 0xbfb8aa3b, v73
	v_exp_f32_e32 v74, v74
	v_exp_f32_e32 v75, v75
	v_lshlrev_b32_e32 v76, 16, v98
	v_and_b32_e32 v77, 0xffff0000, v98
	v_add_f32_e32 v74, 1.0, v74
	v_add_f32_e32 v75, 1.0, v75
	v_rcp_f32_e32 v74, v74
	v_rcp_f32_e32 v75, v75
	v_pk_mul_f32 v[68:69], v[68:69], v[76:77]
	v_lshlrev_b32_e32 v76, 16, v99
	v_and_b32_e32 v77, 0xffff0000, v99
	v_pk_mul_f32 v[72:73], v[74:75], v[72:73]
	s_nop 0
	v_pk_mul_f32 v[68:69], v[68:69], v[72:73]
	v_lshlrev_b32_e32 v72, 16, v103
	v_cvt_pk_bf16_f32 v68, v68, v69
	v_mul_f32_e32 v69, 0xbfb8aa3b, v70
	v_exp_f32_e32 v69, v69
	v_and_b32_e32 v73, 0xffff0000, v103
	v_add_f32_e32 v69, 1.0, v69
	v_rcp_f32_e32 v70, v69
	v_mul_f32_e32 v69, 0xbfb8aa3b, v71
	v_exp_f32_e32 v69, v69
	s_nop 0
	v_add_f32_e32 v69, 1.0, v69
	v_rcp_f32_e32 v71, v69
	v_mul_f32_e32 v69, 0xbfb8aa3b, v72
	v_exp_f32_e32 v69, v69
	v_pk_mul_f32 v[70:71], v[70:71], v[76:77]
	v_add_f32_e32 v69, 1.0, v69
	v_rcp_f32_e32 v74, v69
	v_mul_f32_e32 v69, 0xbfb8aa3b, v73
	v_exp_f32_e32 v69, v69
	s_nop 0
	v_add_f32_e32 v69, 1.0, v69
	v_rcp_f32_e32 v75, v69
	s_nop 0
	v_pk_mul_f32 v[72:73], v[74:75], v[72:73]
	s_nop 0
	v_pk_mul_f32 v[70:71], v[70:71], v[72:73]
	v_lshlrev_b32_e32 v74, 16, v100
	v_cvt_pk_bf16_f32 v69, v70, v71
	v_lshlrev_b32_e32 v70, 16, v104
	v_and_b32_e32 v71, 0xffff0000, v104
	v_mul_f32_e32 v72, 0xbfb8aa3b, v70
	v_mul_f32_e32 v73, 0xbfb8aa3b, v71
	v_exp_f32_e32 v72, v72
	v_exp_f32_e32 v73, v73
	v_and_b32_e32 v75, 0xffff0000, v100
	v_pk_mul_f32 v[60:61], v[60:61], v[74:75]
	v_add_f32_e32 v72, 1.0, v72
	v_add_f32_e32 v73, 1.0, v73
	v_rcp_f32_e32 v72, v72
	v_rcp_f32_e32 v73, v73
	v_lshlrev_b32_e32 v74, 16, v101
	v_and_b32_e32 v75, 0xffff0000, v101
	v_pk_mul_f32 v[70:71], v[72:73], v[70:71]
	s_nop 0
	v_pk_mul_f32 v[60:61], v[60:61], v[70:71]
	s_nop 0
	v_cvt_pk_bf16_f32 v70, v60, v61
	v_mul_f32_e32 v60, 0xbfb8aa3b, v62
	v_lshlrev_b32_e32 v62, 16, v105
	v_mul_f32_e32 v71, 0xbfb8aa3b, v62
	v_exp_f32_e32 v71, v71
	v_mul_f32_e32 v61, 0xbfb8aa3b, v63
	v_and_b32_e32 v63, 0xffff0000, v105
	v_exp_f32_e32 v60, v60
	v_add_f32_e32 v71, 1.0, v71
	v_rcp_f32_e32 v72, v71
	v_mul_f32_e32 v71, 0xbfb8aa3b, v63
	v_exp_f32_e32 v61, v61
	v_exp_f32_e32 v71, v71
	v_add_f32_e32 v60, 1.0, v60
	v_rcp_f32_e32 v60, v60
	v_add_f32_e32 v61, 1.0, v61
	v_add_f32_e32 v71, 1.0, v71
	v_rcp_f32_e32 v61, v61
	v_rcp_f32_e32 v73, v71
	v_pk_mul_f32 v[60:61], v[60:61], v[74:75]
	v_pk_mul_f32 v[62:63], v[72:73], v[62:63]
	s_nop 0
	v_pk_mul_f32 v[60:61], v[60:61], v[62:63]
	s_nop 0
	v_cvt_pk_bf16_f32 v71, v60, v61
	v_add_u32_e32 v60, 0x58000, v88
	global_store_dwordx4 v60, v[68:71], s[60:61] offset:1536 nt sc1
	v_mov_b32_e32 v60, 0x100
	s_nop 0
	v_lshl_add_u32 v98, v175, 1, v60
	v_lshlrev_b32_e32 v60, 9, v174
	v_add_u32_e32 v61, v98, v60
	v_add_u32_e32 v99, v61, v60
	global_load_dwordx4 v[88:91], v61, s[62:63] nt
	global_load_dwordx4 v[92:95], v99, s[64:65] nt
	v_add_u32_e32 v61, 0x2000, v60
	v_add_u32_e32 v62, v61, v98
	v_add_u32_e32 v61, v62, v61
	global_load_dwordx4 v[80:83], v62, s[62:63] nt
	global_load_dwordx4 v[84:87], v61, s[64:65] nt
	v_add_u32_e32 v61, 0x4000, v60
	v_add_u32_e32 v68, 0x6000, v60
	v_add_u32_e32 v62, v61, v98
	v_add_u32_e32 v69, v68, v98
	v_add_u32_e32 v61, v62, v61
	v_add_u32_e32 v68, v69, v68
	global_load_dwordx4 v[72:75], v62, s[62:63] nt
	global_load_dwordx4 v[76:79], v61, s[64:65] nt
	s_waitcnt vmcnt(5)
	v_lshlrev_b32_e32 v104, 16, v88
	s_waitcnt vmcnt(4)
	v_lshlrev_b32_e32 v100, 16, v92
	v_and_b32_e32 v101, 0xffff0000, v92
	v_mul_f32_e32 v92, 0xbfb8aa3b, v100
	v_and_b32_e32 v105, 0xffff0000, v88
	v_mul_f32_e32 v88, 0xbfb8aa3b, v101
	v_exp_f32_e32 v92, v92
	v_exp_f32_e32 v88, v88
	v_pk_mul_f32 v[64:65], v[64:65], v[104:105]
	global_load_dwordx4 v[60:63], v69, s[62:63] nt
	v_add_f32_e32 v92, 1.0, v92
	v_add_f32_e32 v88, 1.0, v88
	v_rcp_f32_e32 v102, v92
	v_rcp_f32_e32 v103, v88
	v_lshlrev_b32_e32 v92, 16, v93
	v_and_b32_e32 v93, 0xffff0000, v93
	global_load_dwordx4 v[68:71], v68, s[64:65] nt
	v_pk_mul_f32 v[100:101], v[102:103], v[100:101]
	s_nop 0
	v_pk_mul_f32 v[64:65], v[64:65], v[100:101]
	v_lshlrev_b32_e32 v100, 16, v89
	v_cvt_pk_bf16_f32 v64, v64, v65
	v_mul_f32_e32 v65, 0xbfb8aa3b, v66
	v_exp_f32_e32 v65, v65
	v_and_b32_e32 v101, 0xffff0000, v89
	v_add_f32_e32 v65, 1.0, v65
	v_rcp_f32_e32 v66, v65
	v_mul_f32_e32 v65, 0xbfb8aa3b, v67
	v_exp_f32_e32 v65, v65
	s_nop 0
	v_add_f32_e32 v65, 1.0, v65
	v_rcp_f32_e32 v67, v65
	v_mul_f32_e32 v65, 0xbfb8aa3b, v92
	v_exp_f32_e32 v65, v65
	v_pk_mul_f32 v[66:67], v[66:67], v[100:101]
	v_add_f32_e32 v65, 1.0, v65
	v_rcp_f32_e32 v88, v65
	v_mul_f32_e32 v65, 0xbfb8aa3b, v93
	v_exp_f32_e32 v65, v65
	s_nop 0
	v_add_f32_e32 v65, 1.0, v65
	v_rcp_f32_e32 v89, v65
	s_nop 0
	v_pk_mul_f32 v[88:89], v[88:89], v[92:93]
	s_nop 0
	v_pk_mul_f32 v[66:67], v[66:67], v[88:89]
	v_lshlrev_b32_e32 v92, 16, v90
	v_cvt_pk_bf16_f32 v65, v66, v67
	v_lshlrev_b32_e32 v66, 16, v94
	v_and_b32_e32 v67, 0xffff0000, v94
	v_mul_f32_e32 v88, 0xbfb8aa3b, v66
	v_mul_f32_e32 v89, 0xbfb8aa3b, v67
	v_exp_f32_e32 v88, v88
	v_exp_f32_e32 v89, v89
	v_and_b32_e32 v93, 0xffff0000, v90
	v_pk_mul_f32 v[56:57], v[56:57], v[92:93]
	v_add_f32_e32 v88, 1.0, v88
	v_add_f32_e32 v89, 1.0, v89
	v_rcp_f32_e32 v88, v88
	v_rcp_f32_e32 v89, v89
	v_lshlrev_b32_e32 v90, 16, v91
	v_and_b32_e32 v91, 0xffff0000, v91
	v_pk_mul_f32 v[66:67], v[88:89], v[66:67]
	s_nop 0
	v_pk_mul_f32 v[56:57], v[56:57], v[66:67]
	s_nop 0
	v_cvt_pk_bf16_f32 v66, v56, v57
	v_mul_f32_e32 v56, 0xbfb8aa3b, v58
	v_lshlrev_b32_e32 v58, 16, v95
	v_mul_f32_e32 v67, 0xbfb8aa3b, v58
	v_exp_f32_e32 v67, v67
	v_mul_f32_e32 v57, 0xbfb8aa3b, v59
	v_and_b32_e32 v59, 0xffff0000, v95
	v_exp_f32_e32 v56, v56
	v_add_f32_e32 v67, 1.0, v67
	v_rcp_f32_e32 v88, v67
	v_mul_f32_e32 v67, 0xbfb8aa3b, v59
	v_exp_f32_e32 v57, v57
	v_exp_f32_e32 v67, v67
	v_add_f32_e32 v56, 1.0, v56
	v_rcp_f32_e32 v56, v56
	v_add_f32_e32 v57, 1.0, v57
	v_add_f32_e32 v67, 1.0, v67
	v_rcp_f32_e32 v57, v57
	v_rcp_f32_e32 v89, v67
	v_pk_mul_f32 v[56:57], v[56:57], v[90:91]
	v_pk_mul_f32 v[58:59], v[88:89], v[58:59]
	s_nop 0
	v_pk_mul_f32 v[56:57], v[56:57], v[58:59]
	s_waitcnt vmcnt(4)
; __device__ __forceinline__ float sigm(float v) { return __builtin_amdgcn_rcpf(1.0f + __builtin_amdgcn_exp2f(-LOG2E * v)); }
; __device__ __forceinline__ float bf_lo(unsigned w) { return __uint_as_float(w << 16); }
; __device__ __forceinline__ float silu_f(float v) { return v * __builtin_amdgcn_rcpf(1.0f + __builtin_amdgcn_exp2f(-1.4426950408889634f * v)); }
; __device__ __forceinline__ float bf_hi(unsigned w) { return __uint_as_float(w & 0xffff0000u); }
; __device__ __forceinline__ unsigned cvt_pk_bf16(float lo, float hi) { f32x2_t v = {lo, hi}; bf16x2_t b = __builtin_convertvector(v, bf16x2_t); return __builtin_bit_cast(unsigned, b); }
;     __device__ __forceinline__ void operator()(const f32x4 (&acc)[2][2][4][2], const Unit& u, int wr, int wc, int fr, int fq) const {
;     ...
;                 for (int m = 0; m < 4; ++m) { const unsigned rl = rl0 + (unsigned)(ai * HALF + m * 16);
;                     const u32x4 yg = ygv[m], sg = sgv[m];
;                     const f32x4 v0 = acc[ai][bj][m][0], v1 = acc[ai][bj][m][1];
;                     u32x4 w;
;                     w.x = cvt_pk_bf16(bf_lo(yg.x) * sigm(v0[0]) * silu_f(bf_lo(sg.x)), bf_hi(yg.x) * sigm(v0[1]) * silu_f(bf_hi(sg.x)));
;                     w.y = cvt_pk_bf16(bf_lo(yg.y) * sigm(v0[2]) * silu_f(bf_lo(sg.y)), bf_hi(yg.y) * sigm(v0[3]) * silu_f(bf_hi(sg.y)));
;                     w.z = cvt_pk_bf16(bf_lo(yg.z) * sigm(v1[0]) * silu_f(bf_lo(sg.z)), bf_hi(yg.z) * sigm(v1[1]) * silu_f(bf_hi(sg.z)));
;                     w.w = cvt_pk_bf16(bf_lo(yg.w) * sigm(v1[2]) * silu_f(bf_lo(sg.w)), bf_hi(yg.w) * sigm(v1[3]) * silu_f(bf_hi(sg.w)));
;                     *(u32x4*)(yb + (rl * 1024u + col) * 2u) = w; }
	v_lshlrev_b32_e32 v58, 16, v84
	v_cvt_pk_bf16_f32 v67, v56, v57
	v_mul_f32_e32 v57, 0xbfb8aa3b, v58
	v_exp_f32_e32 v57, v57
	v_lshl_add_u32 v56, v174, 10, v99
	v_and_b32_e32 v59, 0xffff0000, v84
	global_store_dwordx4 v56, v[64:67], s[60:61] offset:1536 nt sc1
	v_add_f32_e32 v57, 1.0, v57
	s_nop 0
	v_rcp_f32_e32 v64, v57
	v_mul_f32_e32 v57, 0xbfb8aa3b, v59
	v_exp_f32_e32 v57, v57
	v_lshlrev_b32_e32 v66, 16, v80
	v_and_b32_e32 v67, 0xffff0000, v80
	v_pk_mul_f32 v[52:53], v[52:53], v[66:67]
	v_add_f32_e32 v57, 1.0, v57
	v_rcp_f32_e32 v65, v57
	v_lshlrev_b32_e32 v66, 16, v81
	v_and_b32_e32 v67, 0xffff0000, v81
	v_pk_mul_f32 v[58:59], v[64:65], v[58:59]
	s_nop 0
	v_pk_mul_f32 v[52:53], v[52:53], v[58:59]
	v_lshlrev_b32_e32 v58, 16, v85
	v_cvt_pk_bf16_f32 v52, v52, v53
	v_mul_f32_e32 v53, 0xbfb8aa3b, v54
	v_exp_f32_e32 v53, v53
	v_and_b32_e32 v59, 0xffff0000, v85
	v_add_f32_e32 v53, 1.0, v53
	v_rcp_f32_e32 v54, v53
	v_mul_f32_e32 v53, 0xbfb8aa3b, v55
	v_exp_f32_e32 v53, v53
	s_nop 0
	v_add_f32_e32 v53, 1.0, v53
	v_rcp_f32_e32 v55, v53
	v_mul_f32_e32 v53, 0xbfb8aa3b, v58
	v_exp_f32_e32 v53, v53
	v_pk_mul_f32 v[54:55], v[54:55], v[66:67]
	v_add_f32_e32 v53, 1.0, v53
	v_rcp_f32_e32 v64, v53
	v_mul_f32_e32 v53, 0xbfb8aa3b, v59
	v_exp_f32_e32 v53, v53
	s_nop 0
	v_add_f32_e32 v53, 1.0, v53
	v_rcp_f32_e32 v65, v53
	s_nop 0
	v_pk_mul_f32 v[58:59], v[64:65], v[58:59]
	s_nop 0
	v_pk_mul_f32 v[54:55], v[54:55], v[58:59]
	v_lshlrev_b32_e32 v64, 16, v82
	v_cvt_pk_bf16_f32 v53, v54, v55
	v_lshlrev_b32_e32 v54, 16, v86
	v_mul_f32_e32 v57, 0xbfb8aa3b, v54
	v_exp_f32_e32 v57, v57
	v_and_b32_e32 v55, 0xffff0000, v86
	v_and_b32_e32 v65, 0xffff0000, v82
	v_pk_mul_f32 v[48:49], v[48:49], v[64:65]
	v_add_f32_e32 v57, 1.0, v57
	v_rcp_f32_e32 v58, v57
	v_mul_f32_e32 v57, 0xbfb8aa3b, v55
	v_exp_f32_e32 v57, v57
	v_lshlrev_b32_e32 v64, 16, v83
	v_and_b32_e32 v65, 0xffff0000, v83
	v_add_f32_e32 v57, 1.0, v57
	v_rcp_f32_e32 v59, v57
	s_nop 0
	v_pk_mul_f32 v[54:55], v[58:59], v[54:55]
	s_nop 0
	v_pk_mul_f32 v[48:49], v[48:49], v[54:55]
	s_nop 0
	v_cvt_pk_bf16_f32 v54, v48, v49
	v_mul_f32_e32 v48, 0xbfb8aa3b, v50
	v_lshlrev_b32_e32 v50, 16, v87
	v_mul_f32_e32 v55, 0xbfb8aa3b, v50
	v_exp_f32_e32 v55, v55
	v_mul_f32_e32 v49, 0xbfb8aa3b, v51
	v_and_b32_e32 v51, 0xffff0000, v87
	v_exp_f32_e32 v48, v48
	v_add_f32_e32 v55, 1.0, v55
	v_rcp_f32_e32 v58, v55
	v_mul_f32_e32 v55, 0xbfb8aa3b, v51
	v_exp_f32_e32 v49, v49
	v_exp_f32_e32 v55, v55
	v_add_f32_e32 v48, 1.0, v48
	v_rcp_f32_e32 v48, v48
	v_add_f32_e32 v49, 1.0, v49
	v_add_f32_e32 v55, 1.0, v55
	v_rcp_f32_e32 v49, v49
	v_rcp_f32_e32 v59, v55
	v_pk_mul_f32 v[48:49], v[48:49], v[64:65]
	v_pk_mul_f32 v[50:51], v[58:59], v[50:51]
	s_nop 0
	v_pk_mul_f32 v[48:49], v[48:49], v[50:51]
	s_nop 0
	v_cvt_pk_bf16_f32 v55, v48, v49
	v_add_u32_e32 v48, 0x8000, v56
	global_store_dwordx4 v48, v[52:55], s[60:61] offset:1536 nt sc1
	s_waitcnt vmcnt(4)
	v_lshlrev_b32_e32 v48, 16, v76
	v_and_b32_e32 v49, 0xffff0000, v76
	v_mul_f32_e32 v50, 0xbfb8aa3b, v48
	v_mul_f32_e32 v51, 0xbfb8aa3b, v49
	v_exp_f32_e32 v50, v50
	v_exp_f32_e32 v51, v51
	v_lshlrev_b32_e32 v52, 16, v72
	v_and_b32_e32 v53, 0xffff0000, v72
	v_add_f32_e32 v50, 1.0, v50
	v_add_f32_e32 v51, 1.0, v51
	v_rcp_f32_e32 v50, v50
	v_rcp_f32_e32 v51, v51
	v_pk_mul_f32 v[44:45], v[44:45], v[52:53]
	v_lshlrev_b32_e32 v52, 16, v73
	v_and_b32_e32 v53, 0xffff0000, v73
	v_pk_mul_f32 v[48:49], v[50:51], v[48:49]
	s_nop 0
	v_pk_mul_f32 v[44:45], v[44:45], v[48:49]
	v_lshlrev_b32_e32 v48, 16, v77
	v_cvt_pk_bf16_f32 v44, v44, v45
	v_mul_f32_e32 v45, 0xbfb8aa3b, v46
	v_exp_f32_e32 v45, v45
	v_and_b32_e32 v49, 0xffff0000, v77
	v_add_f32_e32 v45, 1.0, v45
	v_rcp_f32_e32 v46, v45
	v_mul_f32_e32 v45, 0xbfb8aa3b, v47
	v_exp_f32_e32 v45, v45
	s_nop 0
	v_add_f32_e32 v45, 1.0, v45
	v_rcp_f32_e32 v47, v45
	v_mul_f32_e32 v45, 0xbfb8aa3b, v48
	v_exp_f32_e32 v45, v45
	v_pk_mul_f32 v[46:47], v[46:47], v[52:53]
	v_add_f32_e32 v45, 1.0, v45
	v_rcp_f32_e32 v50, v45
	v_mul_f32_e32 v45, 0xbfb8aa3b, v49
	v_exp_f32_e32 v45, v45
	s_nop 0
	v_add_f32_e32 v45, 1.0, v45
	v_rcp_f32_e32 v51, v45
	s_nop 0
	v_pk_mul_f32 v[48:49], v[50:51], v[48:49]
	s_nop 0
	v_pk_mul_f32 v[46:47], v[46:47], v[48:49]
	v_lshlrev_b32_e32 v50, 16, v74
	v_cvt_pk_bf16_f32 v45, v46, v47
	v_lshlrev_b32_e32 v46, 16, v78
	v_and_b32_e32 v47, 0xffff0000, v78
	v_mul_f32_e32 v48, 0xbfb8aa3b, v46
	v_mul_f32_e32 v49, 0xbfb8aa3b, v47
	v_exp_f32_e32 v48, v48
	v_exp_f32_e32 v49, v49
	v_and_b32_e32 v51, 0xffff0000, v74
	v_pk_mul_f32 v[40:41], v[40:41], v[50:51]
	v_add_f32_e32 v48, 1.0, v48
	v_add_f32_e32 v49, 1.0, v49
	v_rcp_f32_e32 v48, v48
	v_rcp_f32_e32 v49, v49
	v_lshlrev_b32_e32 v50, 16, v75
	v_and_b32_e32 v51, 0xffff0000, v75
	v_pk_mul_f32 v[46:47], v[48:49], v[46:47]
	s_nop 0
	v_pk_mul_f32 v[40:41], v[40:41], v[46:47]
	s_nop 0
	v_cvt_pk_bf16_f32 v46, v40, v41
	v_mul_f32_e32 v40, 0xbfb8aa3b, v42
	v_lshlrev_b32_e32 v42, 16, v79
	v_mul_f32_e32 v47, 0xbfb8aa3b, v42
	v_exp_f32_e32 v47, v47
	v_mul_f32_e32 v41, 0xbfb8aa3b, v43
	v_and_b32_e32 v43, 0xffff0000, v79
	v_exp_f32_e32 v40, v40
	v_add_f32_e32 v47, 1.0, v47
	v_rcp_f32_e32 v48, v47
	v_mul_f32_e32 v47, 0xbfb8aa3b, v43
	v_exp_f32_e32 v41, v41
	v_exp_f32_e32 v47, v47
	v_add_f32_e32 v40, 1.0, v40
	v_rcp_f32_e32 v40, v40
	v_add_f32_e32 v41, 1.0, v41
	v_add_f32_e32 v47, 1.0, v47
	v_rcp_f32_e32 v41, v41
	v_rcp_f32_e32 v49, v47
	v_pk_mul_f32 v[40:41], v[40:41], v[50:51]
	v_pk_mul_f32 v[42:43], v[48:49], v[42:43]
	s_nop 0
	v_pk_mul_f32 v[40:41], v[40:41], v[42:43]
	s_nop 0
	v_cvt_pk_bf16_f32 v47, v40, v41
	v_add_u32_e32 v40, 0x10000, v56
	global_store_dwordx4 v40, v[44:47], s[60:61] offset:1536 nt sc1
	s_waitcnt vmcnt(3)
; __device__ __forceinline__ float sigm(float v) { return __builtin_amdgcn_rcpf(1.0f + __builtin_amdgcn_exp2f(-LOG2E * v)); }
; __device__ __forceinline__ float bf_lo(unsigned w) { return __uint_as_float(w << 16); }
; __device__ __forceinline__ float silu_f(float v) { return v * __builtin_amdgcn_rcpf(1.0f + __builtin_amdgcn_exp2f(-1.4426950408889634f * v)); }
; __device__ __forceinline__ float bf_hi(unsigned w) { return __uint_as_float(w & 0xffff0000u); }
; __device__ __forceinline__ unsigned cvt_pk_bf16(float lo, float hi) { f32x2_t v = {lo, hi}; bf16x2_t b = __builtin_convertvector(v, bf16x2_t); return __builtin_bit_cast(unsigned, b); }
;     __device__ __forceinline__ void operator()(const f32x4 (&acc)[2][2][4][2], const Unit& u, int wr, int wc, int fr, int fq) const {
;     ...
;         for (int bj = 0; bj < 2; ++bj) { const unsigned col = col0 + bj * HALF;
; #pragma unroll
;             for (int ai = 0; ai < 2; ++ai) {
;                 u32x4 ygv[4], sgv[4];
; #pragma unroll
;                 for (int m = 0; m < 4; ++m) { const unsigned rl = rl0 + (unsigned)(ai * HALF + m * 16);
;                     ygv[m] = *(const u32x4*)(ygb + (rl * 256u + col) * 2u); sgv[m] = *(const u32x4*)(sgb + (rl * 512u + col) * 2u); }
; #pragma unroll
;                 for (int m = 0; m < 4; ++m) { const unsigned rl = rl0 + (unsigned)(ai * HALF + m * 16);
;                     const u32x4 yg = ygv[m], sg = sgv[m];
;                     const f32x4 v0 = acc[ai][bj][m][0], v1 = acc[ai][bj][m][1];
;                     u32x4 w;
;                     w.x = cvt_pk_bf16(bf_lo(yg.x) * sigm(v0[0]) * silu_f(bf_lo(sg.x)), bf_hi(yg.x) * sigm(v0[1]) * silu_f(bf_hi(sg.x)));
;                     w.y = cvt_pk_bf16(bf_lo(yg.y) * sigm(v0[2]) * silu_f(bf_lo(sg.y)), bf_hi(yg.y) * sigm(v0[3]) * silu_f(bf_hi(sg.y)));
;                     w.z = cvt_pk_bf16(bf_lo(yg.z) * sigm(v1[0]) * silu_f(bf_lo(sg.z)), bf_hi(yg.z) * sigm(v1[1]) * silu_f(bf_hi(sg.z)));
;                     w.w = cvt_pk_bf16(bf_lo(yg.w) * sigm(v1[2]) * silu_f(bf_lo(sg.w)), bf_hi(yg.w) * sigm(v1[3]) * silu_f(bf_hi(sg.w)));
;                     *(u32x4*)(yb + (rl * 1024u + col) * 2u) = w; }
	v_lshlrev_b32_e32 v40, 16, v68
	v_and_b32_e32 v41, 0xffff0000, v68
	v_mul_f32_e32 v42, 0xbfb8aa3b, v40
	v_mul_f32_e32 v43, 0xbfb8aa3b, v41
	v_exp_f32_e32 v42, v42
	v_exp_f32_e32 v43, v43
	v_lshlrev_b32_e32 v44, 16, v60
	v_and_b32_e32 v45, 0xffff0000, v60
	v_add_f32_e32 v42, 1.0, v42
	v_add_f32_e32 v43, 1.0, v43
	v_rcp_f32_e32 v42, v42
	v_rcp_f32_e32 v43, v43
	v_pk_mul_f32 v[36:37], v[36:37], v[44:45]
	v_lshlrev_b32_e32 v44, 16, v61
	v_and_b32_e32 v45, 0xffff0000, v61
	v_pk_mul_f32 v[40:41], v[42:43], v[40:41]
	s_nop 0
	v_pk_mul_f32 v[36:37], v[36:37], v[40:41]
	v_lshlrev_b32_e32 v40, 16, v69
	v_cvt_pk_bf16_f32 v36, v36, v37
	v_mul_f32_e32 v37, 0xbfb8aa3b, v38
	v_exp_f32_e32 v37, v37
	v_and_b32_e32 v41, 0xffff0000, v69
	v_add_f32_e32 v37, 1.0, v37
	v_rcp_f32_e32 v38, v37
	v_mul_f32_e32 v37, 0xbfb8aa3b, v39
	v_exp_f32_e32 v37, v37
	s_nop 0
	v_add_f32_e32 v37, 1.0, v37
	v_rcp_f32_e32 v39, v37
	v_mul_f32_e32 v37, 0xbfb8aa3b, v40
	v_exp_f32_e32 v37, v37
	v_pk_mul_f32 v[38:39], v[38:39], v[44:45]
	v_add_f32_e32 v37, 1.0, v37
	v_rcp_f32_e32 v42, v37
	v_mul_f32_e32 v37, 0xbfb8aa3b, v41
	v_exp_f32_e32 v37, v37
	s_nop 0
	v_add_f32_e32 v37, 1.0, v37
	v_rcp_f32_e32 v43, v37
	s_nop 0
	v_pk_mul_f32 v[40:41], v[42:43], v[40:41]
	s_nop 0
	v_pk_mul_f32 v[38:39], v[38:39], v[40:41]
	v_lshlrev_b32_e32 v42, 16, v62
	v_cvt_pk_bf16_f32 v37, v38, v39
	v_lshlrev_b32_e32 v38, 16, v70
	v_and_b32_e32 v39, 0xffff0000, v70
	v_mul_f32_e32 v40, 0xbfb8aa3b, v38
	v_mul_f32_e32 v41, 0xbfb8aa3b, v39
	v_exp_f32_e32 v40, v40
	v_exp_f32_e32 v41, v41
	v_and_b32_e32 v43, 0xffff0000, v62
	v_pk_mul_f32 v[32:33], v[32:33], v[42:43]
	v_add_f32_e32 v40, 1.0, v40
	v_add_f32_e32 v41, 1.0, v41
	v_rcp_f32_e32 v40, v40
	v_rcp_f32_e32 v41, v41
	v_lshlrev_b32_e32 v42, 16, v63
	v_and_b32_e32 v43, 0xffff0000, v63
	v_pk_mul_f32 v[38:39], v[40:41], v[38:39]
	s_nop 0
	v_pk_mul_f32 v[32:33], v[32:33], v[38:39]
	s_nop 0
	v_cvt_pk_bf16_f32 v38, v32, v33
	v_mul_f32_e32 v32, 0xbfb8aa3b, v34
	v_lshlrev_b32_e32 v34, 16, v71
	v_mul_f32_e32 v39, 0xbfb8aa3b, v34
	v_exp_f32_e32 v39, v39
	v_mul_f32_e32 v33, 0xbfb8aa3b, v35
	v_and_b32_e32 v35, 0xffff0000, v71
	v_exp_f32_e32 v32, v32
	v_add_f32_e32 v39, 1.0, v39
	v_rcp_f32_e32 v40, v39
	v_mul_f32_e32 v39, 0xbfb8aa3b, v35
	v_exp_f32_e32 v33, v33
	v_exp_f32_e32 v39, v39
	v_add_f32_e32 v32, 1.0, v32
	v_rcp_f32_e32 v32, v32
	v_add_f32_e32 v33, 1.0, v33
	v_add_f32_e32 v39, 1.0, v39
	v_rcp_f32_e32 v33, v33
	v_rcp_f32_e32 v41, v39
	v_pk_mul_f32 v[32:33], v[32:33], v[42:43]
	v_pk_mul_f32 v[34:35], v[40:41], v[34:35]
	s_nop 0
	v_pk_mul_f32 v[32:33], v[32:33], v[34:35]
	s_nop 0
	v_cvt_pk_bf16_f32 v39, v32, v33
	v_add_u32_e32 v32, 0x18000, v56
	global_store_dwordx4 v32, v[36:39], s[60:61] offset:1536 nt sc1
	s_nop 0
	v_lshlrev_b32_e32 v32, 9, v174
	v_add_u32_e32 v33, 0x10000, v32
	v_add_u32_e32 v34, v33, v98
	v_add_u32_e32 v33, v34, v33
	global_load_dwordx4 v[56:59], v34, s[62:63] nt
	global_load_dwordx4 v[60:63], v33, s[64:65] nt
	v_add_u32_e32 v33, 0x12000, v32
	v_add_u32_e32 v34, v33, v98
	v_add_u32_e32 v33, v34, v33
	global_load_dwordx4 v[48:51], v34, s[62:63] nt
	global_load_dwordx4 v[52:55], v33, s[64:65] nt
	v_add_u32_e32 v33, 0x14000, v32
	v_add_u32_e32 v36, 0x16000, v32
	v_add_u32_e32 v34, v33, v98
	v_add_u32_e32 v37, v36, v98
	v_add_u32_e32 v33, v34, v33
	v_add_u32_e32 v36, v37, v36
	global_load_dwordx4 v[40:43], v34, s[62:63] nt
	global_load_dwordx4 v[44:47], v33, s[64:65] nt
	s_waitcnt vmcnt(5)
	v_lshlrev_b32_e32 v68, 16, v56
	s_waitcnt vmcnt(4)
	v_lshlrev_b32_e32 v64, 16, v60
	v_and_b32_e32 v65, 0xffff0000, v60
	v_mul_f32_e32 v60, 0xbfb8aa3b, v64
	v_and_b32_e32 v69, 0xffff0000, v56
	v_mul_f32_e32 v56, 0xbfb8aa3b, v65
	v_exp_f32_e32 v60, v60
	v_exp_f32_e32 v56, v56
	v_pk_mul_f32 v[28:29], v[28:29], v[68:69]
	global_load_dwordx4 v[32:35], v37, s[62:63] nt
	v_add_f32_e32 v60, 1.0, v60
	v_add_f32_e32 v56, 1.0, v56
	v_rcp_f32_e32 v66, v60
	v_rcp_f32_e32 v67, v56
	v_lshlrev_b32_e32 v60, 16, v61
	v_and_b32_e32 v61, 0xffff0000, v61
	global_load_dwordx4 v[36:39], v36, s[64:65] nt
	v_pk_mul_f32 v[64:65], v[66:67], v[64:65]
	s_nop 0
	v_pk_mul_f32 v[28:29], v[28:29], v[64:65]
	v_lshlrev_b32_e32 v64, 16, v57
	v_cvt_pk_bf16_f32 v28, v28, v29
	v_mul_f32_e32 v29, 0xbfb8aa3b, v30
	v_exp_f32_e32 v29, v29
	v_and_b32_e32 v65, 0xffff0000, v57
	v_add_f32_e32 v29, 1.0, v29
	v_rcp_f32_e32 v30, v29
	v_mul_f32_e32 v29, 0xbfb8aa3b, v31
	v_exp_f32_e32 v29, v29
	s_nop 0
	v_add_f32_e32 v29, 1.0, v29
	v_rcp_f32_e32 v31, v29
	v_mul_f32_e32 v29, 0xbfb8aa3b, v60
	v_exp_f32_e32 v29, v29
	v_pk_mul_f32 v[30:31], v[30:31], v[64:65]
	v_add_f32_e32 v29, 1.0, v29
	v_rcp_f32_e32 v56, v29
	v_mul_f32_e32 v29, 0xbfb8aa3b, v61
	v_exp_f32_e32 v29, v29
	s_nop 0
	v_add_f32_e32 v29, 1.0, v29
	v_rcp_f32_e32 v57, v29
	s_nop 0
	v_pk_mul_f32 v[56:57], v[56:57], v[60:61]
	s_nop 0
	v_pk_mul_f32 v[30:31], v[30:31], v[56:57]
	v_lshlrev_b32_e32 v60, 16, v58
	v_cvt_pk_bf16_f32 v29, v30, v31
	v_lshlrev_b32_e32 v30, 16, v62
	v_and_b32_e32 v31, 0xffff0000, v62
	v_mul_f32_e32 v56, 0xbfb8aa3b, v30
	v_mul_f32_e32 v57, 0xbfb8aa3b, v31
	v_exp_f32_e32 v56, v56
	v_exp_f32_e32 v57, v57
	v_and_b32_e32 v61, 0xffff0000, v58
	v_pk_mul_f32 v[24:25], v[24:25], v[60:61]
	v_add_f32_e32 v56, 1.0, v56
	v_add_f32_e32 v57, 1.0, v57
	v_rcp_f32_e32 v56, v56
	v_rcp_f32_e32 v57, v57
	v_lshlrev_b32_e32 v58, 16, v59
	v_and_b32_e32 v59, 0xffff0000, v59
	v_pk_mul_f32 v[30:31], v[56:57], v[30:31]
	s_nop 0
	v_pk_mul_f32 v[24:25], v[24:25], v[30:31]
	s_nop 0
	v_cvt_pk_bf16_f32 v30, v24, v25
	v_mul_f32_e32 v24, 0xbfb8aa3b, v26
	v_lshlrev_b32_e32 v26, 16, v63
	v_mul_f32_e32 v31, 0xbfb8aa3b, v26
	v_exp_f32_e32 v31, v31
	v_mul_f32_e32 v25, 0xbfb8aa3b, v27
	v_and_b32_e32 v27, 0xffff0000, v63
	v_exp_f32_e32 v24, v24
	v_add_f32_e32 v31, 1.0, v31
	v_rcp_f32_e32 v56, v31
	v_mul_f32_e32 v31, 0xbfb8aa3b, v27
	v_exp_f32_e32 v25, v25
	v_exp_f32_e32 v31, v31
	v_add_f32_e32 v24, 1.0, v24
	v_rcp_f32_e32 v24, v24
	v_add_f32_e32 v25, 1.0, v25
	v_add_f32_e32 v31, 1.0, v31
	v_rcp_f32_e32 v25, v25
	v_rcp_f32_e32 v57, v31
	v_pk_mul_f32 v[24:25], v[24:25], v[58:59]
	v_pk_mul_f32 v[26:27], v[56:57], v[26:27]
	s_nop 0
	v_pk_mul_f32 v[24:25], v[24:25], v[26:27]
	s_waitcnt vmcnt(4)
; __device__ __forceinline__ float sigm(float v) { return __builtin_amdgcn_rcpf(1.0f + __builtin_amdgcn_exp2f(-LOG2E * v)); }
; __device__ __forceinline__ float bf_lo(unsigned w) { return __uint_as_float(w << 16); }
; __device__ __forceinline__ float silu_f(float v) { return v * __builtin_amdgcn_rcpf(1.0f + __builtin_amdgcn_exp2f(-1.4426950408889634f * v)); }
; __device__ __forceinline__ float bf_hi(unsigned w) { return __uint_as_float(w & 0xffff0000u); }
; __device__ __forceinline__ unsigned cvt_pk_bf16(float lo, float hi) { f32x2_t v = {lo, hi}; bf16x2_t b = __builtin_convertvector(v, bf16x2_t); return __builtin_bit_cast(unsigned, b); }
;     __device__ __forceinline__ void operator()(const f32x4 (&acc)[2][2][4][2], const Unit& u, int wr, int wc, int fr, int fq) const {
;     ...
;                 for (int m = 0; m < 4; ++m) { const unsigned rl = rl0 + (unsigned)(ai * HALF + m * 16);
;                     const u32x4 yg = ygv[m], sg = sgv[m];
;                     const f32x4 v0 = acc[ai][bj][m][0], v1 = acc[ai][bj][m][1];
;                     u32x4 w;
;                     w.x = cvt_pk_bf16(bf_lo(yg.x) * sigm(v0[0]) * silu_f(bf_lo(sg.x)), bf_hi(yg.x) * sigm(v0[1]) * silu_f(bf_hi(sg.x)));
;                     w.y = cvt_pk_bf16(bf_lo(yg.y) * sigm(v0[2]) * silu_f(bf_lo(sg.y)), bf_hi(yg.y) * sigm(v0[3]) * silu_f(bf_hi(sg.y)));
;                     w.z = cvt_pk_bf16(bf_lo(yg.z) * sigm(v1[0]) * silu_f(bf_lo(sg.z)), bf_hi(yg.z) * sigm(v1[1]) * silu_f(bf_hi(sg.z)));
;                     w.w = cvt_pk_bf16(bf_lo(yg.w) * sigm(v1[2]) * silu_f(bf_lo(sg.w)), bf_hi(yg.w) * sigm(v1[3]) * silu_f(bf_hi(sg.w)));
;                     *(u32x4*)(yb + (rl * 1024u + col) * 2u) = w; }
	v_lshlrev_b32_e32 v26, 16, v52
	v_cvt_pk_bf16_f32 v31, v24, v25
	v_lshl_add_u32 v24, v174, 11, v98
	v_add_u32_e32 v25, 0x40000, v24
	global_store_dwordx4 v25, v[28:31], s[60:61] offset:1536 nt sc1
	v_mul_f32_e32 v25, 0xbfb8aa3b, v26
	v_exp_f32_e32 v25, v25
	v_and_b32_e32 v27, 0xffff0000, v52
	v_lshlrev_b32_e32 v30, 16, v48
	v_and_b32_e32 v31, 0xffff0000, v48
	v_add_f32_e32 v25, 1.0, v25
	v_rcp_f32_e32 v28, v25
	v_mul_f32_e32 v25, 0xbfb8aa3b, v27
	v_exp_f32_e32 v25, v25
	v_pk_mul_f32 v[20:21], v[20:21], v[30:31]
	v_lshlrev_b32_e32 v30, 16, v49
	v_and_b32_e32 v31, 0xffff0000, v49
	v_add_f32_e32 v25, 1.0, v25
	v_rcp_f32_e32 v29, v25
	s_nop 0
	v_pk_mul_f32 v[26:27], v[28:29], v[26:27]
	s_nop 0
	v_pk_mul_f32 v[20:21], v[20:21], v[26:27]
	v_lshlrev_b32_e32 v26, 16, v53
	v_cvt_pk_bf16_f32 v20, v20, v21
	v_mul_f32_e32 v21, 0xbfb8aa3b, v22
	v_exp_f32_e32 v21, v21
	v_and_b32_e32 v27, 0xffff0000, v53
	v_add_f32_e32 v21, 1.0, v21
	v_rcp_f32_e32 v22, v21
	v_mul_f32_e32 v21, 0xbfb8aa3b, v23
	v_exp_f32_e32 v21, v21
	s_nop 0
	v_add_f32_e32 v21, 1.0, v21
	v_rcp_f32_e32 v23, v21
	v_mul_f32_e32 v21, 0xbfb8aa3b, v26
	v_exp_f32_e32 v21, v21
	v_pk_mul_f32 v[22:23], v[22:23], v[30:31]
	v_add_f32_e32 v21, 1.0, v21
	v_rcp_f32_e32 v28, v21
	v_mul_f32_e32 v21, 0xbfb8aa3b, v27
	v_exp_f32_e32 v21, v21
	s_nop 0
	v_add_f32_e32 v21, 1.0, v21
	v_rcp_f32_e32 v29, v21
	s_nop 0
	v_pk_mul_f32 v[26:27], v[28:29], v[26:27]
	s_nop 0
	v_pk_mul_f32 v[22:23], v[22:23], v[26:27]
	v_lshlrev_b32_e32 v28, 16, v50
	v_cvt_pk_bf16_f32 v21, v22, v23
	v_lshlrev_b32_e32 v22, 16, v54
	v_mul_f32_e32 v25, 0xbfb8aa3b, v22
	v_exp_f32_e32 v25, v25
	v_and_b32_e32 v23, 0xffff0000, v54
	v_and_b32_e32 v29, 0xffff0000, v50
	v_pk_mul_f32 v[16:17], v[16:17], v[28:29]
	v_add_f32_e32 v25, 1.0, v25
	v_rcp_f32_e32 v26, v25
	v_mul_f32_e32 v25, 0xbfb8aa3b, v23
	v_exp_f32_e32 v25, v25
	v_lshlrev_b32_e32 v28, 16, v51
	v_and_b32_e32 v29, 0xffff0000, v51
	v_add_f32_e32 v25, 1.0, v25
	v_rcp_f32_e32 v27, v25
	s_nop 0
	v_pk_mul_f32 v[22:23], v[26:27], v[22:23]
	s_nop 0
	v_pk_mul_f32 v[16:17], v[16:17], v[22:23]
	s_nop 0
	v_cvt_pk_bf16_f32 v22, v16, v17
	v_mul_f32_e32 v16, 0xbfb8aa3b, v18
	v_lshlrev_b32_e32 v18, 16, v55
	v_mul_f32_e32 v23, 0xbfb8aa3b, v18
	v_exp_f32_e32 v23, v23
	v_mul_f32_e32 v17, 0xbfb8aa3b, v19
	v_and_b32_e32 v19, 0xffff0000, v55
	v_exp_f32_e32 v16, v16
	v_add_f32_e32 v23, 1.0, v23
	v_rcp_f32_e32 v26, v23
	v_mul_f32_e32 v23, 0xbfb8aa3b, v19
	v_exp_f32_e32 v17, v17
	v_exp_f32_e32 v23, v23
	v_add_f32_e32 v16, 1.0, v16
	v_rcp_f32_e32 v16, v16
	v_add_f32_e32 v17, 1.0, v17
	v_add_f32_e32 v23, 1.0, v23
	v_rcp_f32_e32 v17, v17
	v_rcp_f32_e32 v27, v23
	v_pk_mul_f32 v[16:17], v[16:17], v[28:29]
	v_pk_mul_f32 v[18:19], v[26:27], v[18:19]
	s_nop 0
	v_pk_mul_f32 v[16:17], v[16:17], v[18:19]
	s_nop 0
	v_cvt_pk_bf16_f32 v23, v16, v17
	v_add_u32_e32 v16, 0x48000, v24
	global_store_dwordx4 v16, v[20:23], s[60:61] offset:1536 nt sc1
	s_waitcnt vmcnt(4)
	v_lshlrev_b32_e32 v16, 16, v44
	v_and_b32_e32 v17, 0xffff0000, v44
	v_mul_f32_e32 v18, 0xbfb8aa3b, v16
	v_mul_f32_e32 v19, 0xbfb8aa3b, v17
	v_exp_f32_e32 v18, v18
	v_exp_f32_e32 v19, v19
	v_lshlrev_b32_e32 v20, 16, v40
	v_and_b32_e32 v21, 0xffff0000, v40
	v_add_f32_e32 v18, 1.0, v18
	v_add_f32_e32 v19, 1.0, v19
	v_rcp_f32_e32 v18, v18
	v_rcp_f32_e32 v19, v19
	v_pk_mul_f32 v[12:13], v[12:13], v[20:21]
	v_lshlrev_b32_e32 v20, 16, v41
	v_and_b32_e32 v21, 0xffff0000, v41
	v_pk_mul_f32 v[16:17], v[18:19], v[16:17]
	s_nop 0
	v_pk_mul_f32 v[12:13], v[12:13], v[16:17]
	v_lshlrev_b32_e32 v16, 16, v45
	v_cvt_pk_bf16_f32 v12, v12, v13
	v_mul_f32_e32 v13, 0xbfb8aa3b, v14
	v_exp_f32_e32 v13, v13
	v_and_b32_e32 v17, 0xffff0000, v45
	v_add_f32_e32 v13, 1.0, v13
	v_rcp_f32_e32 v14, v13
	v_mul_f32_e32 v13, 0xbfb8aa3b, v15
	v_exp_f32_e32 v13, v13
	s_nop 0
	v_add_f32_e32 v13, 1.0, v13
	v_rcp_f32_e32 v15, v13
	v_mul_f32_e32 v13, 0xbfb8aa3b, v16
	v_exp_f32_e32 v13, v13
	v_pk_mul_f32 v[14:15], v[14:15], v[20:21]
	v_add_f32_e32 v13, 1.0, v13
	v_rcp_f32_e32 v18, v13
	v_mul_f32_e32 v13, 0xbfb8aa3b, v17
	v_exp_f32_e32 v13, v13
	s_nop 0
	v_add_f32_e32 v13, 1.0, v13
	v_rcp_f32_e32 v19, v13
	s_nop 0
	v_pk_mul_f32 v[16:17], v[18:19], v[16:17]
	s_nop 0
	v_pk_mul_f32 v[14:15], v[14:15], v[16:17]
	v_lshlrev_b32_e32 v18, 16, v42
	v_cvt_pk_bf16_f32 v13, v14, v15
	v_lshlrev_b32_e32 v14, 16, v46
	v_and_b32_e32 v15, 0xffff0000, v46
	v_mul_f32_e32 v16, 0xbfb8aa3b, v14
	v_mul_f32_e32 v17, 0xbfb8aa3b, v15
	v_exp_f32_e32 v16, v16
	v_exp_f32_e32 v17, v17
	v_and_b32_e32 v19, 0xffff0000, v42
	v_pk_mul_f32 v[8:9], v[8:9], v[18:19]
	v_add_f32_e32 v16, 1.0, v16
	v_add_f32_e32 v17, 1.0, v17
	v_rcp_f32_e32 v16, v16
	v_rcp_f32_e32 v17, v17
	v_lshlrev_b32_e32 v18, 16, v43
	v_and_b32_e32 v19, 0xffff0000, v43
	v_pk_mul_f32 v[14:15], v[16:17], v[14:15]
	s_nop 0
	v_pk_mul_f32 v[8:9], v[8:9], v[14:15]
	s_nop 0
	v_cvt_pk_bf16_f32 v14, v8, v9
	v_mul_f32_e32 v8, 0xbfb8aa3b, v10
	v_lshlrev_b32_e32 v10, 16, v47
	v_mul_f32_e32 v15, 0xbfb8aa3b, v10
	v_exp_f32_e32 v15, v15
	v_mul_f32_e32 v9, 0xbfb8aa3b, v11
	v_and_b32_e32 v11, 0xffff0000, v47
	v_exp_f32_e32 v8, v8
	v_add_f32_e32 v15, 1.0, v15
	v_rcp_f32_e32 v16, v15
	v_mul_f32_e32 v15, 0xbfb8aa3b, v11
	v_exp_f32_e32 v9, v9
	v_exp_f32_e32 v15, v15
	v_add_f32_e32 v8, 1.0, v8
	v_rcp_f32_e32 v8, v8
	v_add_f32_e32 v9, 1.0, v9
	v_add_f32_e32 v15, 1.0, v15
	v_rcp_f32_e32 v9, v9
	v_rcp_f32_e32 v17, v15
	v_pk_mul_f32 v[8:9], v[8:9], v[18:19]
	v_pk_mul_f32 v[10:11], v[16:17], v[10:11]
	s_nop 0
	v_pk_mul_f32 v[8:9], v[8:9], v[10:11]
	s_nop 0
	v_cvt_pk_bf16_f32 v15, v8, v9
	v_add_u32_e32 v8, 0x50000, v24
	global_store_dwordx4 v8, v[12:15], s[60:61] offset:1536 nt sc1
	s_waitcnt vmcnt(3)
; __device__ __forceinline__ float sigm(float v) { return __builtin_amdgcn_rcpf(1.0f + __builtin_amdgcn_exp2f(-LOG2E * v)); }
; __device__ __forceinline__ float bf_lo(unsigned w) { return __uint_as_float(w << 16); }
; __device__ __forceinline__ float silu_f(float v) { return v * __builtin_amdgcn_rcpf(1.0f + __builtin_amdgcn_exp2f(-1.4426950408889634f * v)); }
; __device__ __forceinline__ float bf_hi(unsigned w) { return __uint_as_float(w & 0xffff0000u); }
; __device__ __forceinline__ unsigned cvt_pk_bf16(float lo, float hi) { f32x2_t v = {lo, hi}; bf16x2_t b = __builtin_convertvector(v, bf16x2_t); return __builtin_bit_cast(unsigned, b); }
;     __device__ __forceinline__ void acc_init(f32x4 (&ini)[2][2], const Unit& u) const {
;         int t__ = threadIdx.x; asm volatile("" : "+v"(t__)); const int wid__ = __builtin_amdgcn_readfirstlane(t__ >> 6), wc = wid__ & 3, fq = (t__ & 63) >> 4;
;         const float* bp = bias + wc * 32 + 8 * fq; (void)u;
; #pragma unroll
;         for (int bj = 0; bj < 2; ++bj)
; #pragma unroll
;             for (int n = 0; n < 2; ++n) ini[bj][n] = *(const f32x4*)(bp + bj * HALF + 4 * n);
;     __device__ __forceinline__ void operator()(const f32x4 (&acc)[2][2][4][2], const Unit& u, int wr, int wc, int fr, int fq) const {
;     ...
;                 for (int m = 0; m < 4; ++m) { const unsigned rl = rl0 + (unsigned)(ai * HALF + m * 16);
;                     const u32x4 yg = ygv[m], sg = sgv[m];
;                     const f32x4 v0 = acc[ai][bj][m][0], v1 = acc[ai][bj][m][1];
;                     u32x4 w;
;                     w.x = cvt_pk_bf16(bf_lo(yg.x) * sigm(v0[0]) * silu_f(bf_lo(sg.x)), bf_hi(yg.x) * sigm(v0[1]) * silu_f(bf_hi(sg.x)));
;                     w.y = cvt_pk_bf16(bf_lo(yg.y) * sigm(v0[2]) * silu_f(bf_lo(sg.y)), bf_hi(yg.y) * sigm(v0[3]) * silu_f(bf_hi(sg.y)));
;                     w.z = cvt_pk_bf16(bf_lo(yg.z) * sigm(v1[0]) * silu_f(bf_lo(sg.z)), bf_hi(yg.z) * sigm(v1[1]) * silu_f(bf_hi(sg.z)));
;                     w.w = cvt_pk_bf16(bf_lo(yg.w) * sigm(v1[2]) * silu_f(bf_lo(sg.w)), bf_hi(yg.w) * sigm(v1[3]) * silu_f(bf_hi(sg.w)));
;                     *(u32x4*)(yb + (rl * 1024u + col) * 2u) = w; }
	v_lshlrev_b32_e32 v8, 16, v36
	v_and_b32_e32 v9, 0xffff0000, v36
	v_mul_f32_e32 v10, 0xbfb8aa3b, v8
	v_mul_f32_e32 v11, 0xbfb8aa3b, v9
	v_exp_f32_e32 v10, v10
	v_exp_f32_e32 v11, v11
	v_lshlrev_b32_e32 v12, 16, v32
	v_and_b32_e32 v13, 0xffff0000, v32
	v_add_f32_e32 v10, 1.0, v10
	v_add_f32_e32 v11, 1.0, v11
	v_rcp_f32_e32 v10, v10
	v_rcp_f32_e32 v11, v11
	v_pk_mul_f32 v[4:5], v[4:5], v[12:13]
	v_lshlrev_b32_e32 v12, 16, v33
	v_and_b32_e32 v13, 0xffff0000, v33
	v_pk_mul_f32 v[8:9], v[10:11], v[8:9]
	s_nop 0
	v_pk_mul_f32 v[4:5], v[4:5], v[8:9]
	v_lshlrev_b32_e32 v8, 16, v37
	v_cvt_pk_bf16_f32 v4, v4, v5
	v_mul_f32_e32 v5, 0xbfb8aa3b, v6
	v_exp_f32_e32 v5, v5
	v_and_b32_e32 v9, 0xffff0000, v37
	v_add_f32_e32 v5, 1.0, v5
	v_rcp_f32_e32 v6, v5
	v_mul_f32_e32 v5, 0xbfb8aa3b, v7
	v_exp_f32_e32 v5, v5
	s_nop 0
	v_add_f32_e32 v5, 1.0, v5
	v_rcp_f32_e32 v7, v5
	v_mul_f32_e32 v5, 0xbfb8aa3b, v8
	v_exp_f32_e32 v5, v5
	v_pk_mul_f32 v[6:7], v[6:7], v[12:13]
	v_add_f32_e32 v5, 1.0, v5
	v_rcp_f32_e32 v10, v5
	v_mul_f32_e32 v5, 0xbfb8aa3b, v9
	v_exp_f32_e32 v5, v5
	s_nop 0
	v_add_f32_e32 v5, 1.0, v5
	v_rcp_f32_e32 v11, v5
	s_nop 0
	v_pk_mul_f32 v[8:9], v[10:11], v[8:9]
	s_nop 0
	v_pk_mul_f32 v[6:7], v[6:7], v[8:9]
	v_lshlrev_b32_e32 v10, 16, v34
	v_cvt_pk_bf16_f32 v5, v6, v7
	v_lshlrev_b32_e32 v6, 16, v38
	v_and_b32_e32 v7, 0xffff0000, v38
	v_mul_f32_e32 v8, 0xbfb8aa3b, v6
	v_mul_f32_e32 v9, 0xbfb8aa3b, v7
	v_exp_f32_e32 v8, v8
	v_exp_f32_e32 v9, v9
	v_and_b32_e32 v11, 0xffff0000, v34
	v_pk_mul_f32 v[0:1], v[0:1], v[10:11]
	v_add_f32_e32 v8, 1.0, v8
	v_add_f32_e32 v9, 1.0, v9
	v_rcp_f32_e32 v8, v8
	v_rcp_f32_e32 v9, v9
	v_lshlrev_b32_e32 v10, 16, v35
	v_and_b32_e32 v11, 0xffff0000, v35
	v_pk_mul_f32 v[6:7], v[8:9], v[6:7]
	s_nop 0
	v_pk_mul_f32 v[0:1], v[0:1], v[6:7]
	s_nop 0
	v_cvt_pk_bf16_f32 v6, v0, v1
	v_mul_f32_e32 v0, 0xbfb8aa3b, v2
	v_lshlrev_b32_e32 v2, 16, v39
	v_mul_f32_e32 v7, 0xbfb8aa3b, v2
	v_exp_f32_e32 v7, v7
	v_mul_f32_e32 v1, 0xbfb8aa3b, v3
	v_and_b32_e32 v3, 0xffff0000, v39
	v_exp_f32_e32 v0, v0
	v_add_f32_e32 v7, 1.0, v7
	v_rcp_f32_e32 v8, v7
	v_mul_f32_e32 v7, 0xbfb8aa3b, v3
	v_exp_f32_e32 v1, v1
	v_exp_f32_e32 v7, v7
	v_add_f32_e32 v0, 1.0, v0
	v_rcp_f32_e32 v0, v0
	v_add_f32_e32 v1, 1.0, v1
	v_add_f32_e32 v7, 1.0, v7
	v_rcp_f32_e32 v1, v1
	v_rcp_f32_e32 v9, v7
	v_pk_mul_f32 v[0:1], v[0:1], v[10:11]
	v_pk_mul_f32 v[2:3], v[8:9], v[2:3]
	s_nop 0
	v_pk_mul_f32 v[0:1], v[0:1], v[2:3]
	s_nop 0
	v_cvt_pk_bf16_f32 v7, v0, v1
	v_add_u32_e32 v0, 0x58000, v24
	global_store_dwordx4 v0, v[4:7], s[60:61] offset:1536 nt sc1
	s_mov_b64 s[60:61], -1
	s_cbranch_vccnz .LBB0_68
	v_mov_b32_e32 v0, v212
	s_nop 0
	v_readfirstlane_b32 s0, v0
	s_lshl_b32 s0, s0, 1
	s_and_b32 s0, s0, 0x180
	s_add_u32 s16, s25, s0
	v_lshlrev_b32_e32 v0, 1, v0
	s_addc_u32 s17, s31, 0
	v_and_b32_e32 v4, 0x60, v0
	global_load_dwordx4 v[60:63], v4, s[16:17] offset:16
	global_load_dwordx4 v[68:71], v4, s[16:17]
	global_load_dwordx4 v[0:3], v4, s[16:17] offset:528
	s_nop 0
	global_load_dwordx4 v[4:7], v4, s[16:17] offset:512
	v_readlane_b32 s16, v252, 52
	v_readlane_b32 s17, v252, 53
	s_andn2_b64 vcc, exec, s[16:17]
	s_cbranch_vccnz .LBB0_67
	s_barrier
	s_branch .LBB0_67

; __device__ __forceinline__ float sigm(float v) { return __builtin_amdgcn_rcpf(1.0f + __builtin_amdgcn_exp2f(-LOG2E * v)); }
; __device__ __forceinline__ unsigned pk_bf16(float lo, float hi) { return pg8::cvt_pk_bf16(lo, hi); }
; #define LDS_FENCE() asm volatile("s_waitcnt lgkmcnt(0)" ::: "memory")
; template <bool PASS2> __device__ __forceinline__ void ssm2_pass(const Ctx& c, int l) {
;     ...
;                     xAr = half_bcast(xAr, ps); xAi = half_bcast(xAi, ps); xBr = half_bcast(xBr, ps); xBi = half_bcast(xBi, ps);
;                 }
;                 if (PASS2 && (gq & 1)) {
;                     LDS_FENCE();
;                     f32x4 a0 = {0.f, 0.f, 0.f, 0.f}, a1 = {0.f, 0.f, 0.f, 0.f};
;                     const unsigned* xp = XP + (lane & 15) * 132 + 4 * (lane >> 4);
; #pragma unroll
;                     for (int s_ = 0; s_ < 8; s_ += 2) {
;                         a0 = __builtin_amdgcn_mfma_f32_16x16x32_bf16(*(const bf16x8*)(xp + 16 * s_), Cb[s_], a0, 0, 0, 0);
;                         a1 = __builtin_amdgcn_mfma_f32_16x16x32_bf16(*(const bf16x8*)(xp + 16 * s_ + 16), Cb[s_ + 1], a1, 0, 0, 0);
;                     }
;                     const int h = lane & 15, t16 = (gq >> 1) * 16;
; #pragma unroll
;                     for (int i = 0; i < 4; ++i) { const int tt = 4 * (lane >> 4) + i;
;                         float y = a0[i] + a1[i] + dsk * Ul[(t16 + tt) * 16 + h];
;                         const float z = 0.7978845608028654f * (y + 0.044715f * y * y * y);
;                         y = y * sigm(2.0f * z);
;                         YG[(row0 + blk * 32 + t16 + tt) * 256 + g * 16 + h] = (bf16_t)(pk_bf16(y, 0.f) & 0xffffu); }
;                     LDS_FENCE();
.LBB0_124:
	s_or_b64 exec, exec, s[44:45]
	v_mov_b32_e32 v166, v4
	v_mov_b32_e32 v168, v6
	v_mov_b32_e32 v167, v5
	v_mov_b32_e32 v169, v7
	v_permlane32_swap_b32_e32 v4, v166
	v_permlane32_swap_b32_e32 v6, v168
	v_permlane32_swap_b32_e32 v5, v167
	v_permlane32_swap_b32_e32 v7, v169
	s_waitcnt lgkmcnt(0)
	ds_read_b128 v[4:7], v171
	ds_read_b128 v[8:11], v171 offset:64
	ds_read_b128 v[12:15], v171 offset:128
	s_waitcnt lgkmcnt(2)
	v_mfma_f32_16x16x32_bf16 v[4:7], v[4:7], v[80:83], 0
	v_add_co_u32_e32 v0, vcc, s1, v0
	s_add_u32 s42, s42, 0x4000
	s_waitcnt lgkmcnt(0)
	v_mfma_f32_16x16x32_bf16 v[4:7], v[12:15], v[88:91], v[4:7]
	ds_read_b128 v[12:15], v171 offset:192
	v_addc_co_u32_e32 v1, vcc, 0, v1, vcc
	v_mfma_f32_16x16x32_bf16 v[8:11], v[8:11], v[84:87], 0
	s_addc_u32 s43, s43, 0
	s_mov_b64 s[44:45], 0x8000
	s_waitcnt vmcnt(4)
	v_mov_b64_e32 v[136:137], v[132:133]
	s_waitcnt lgkmcnt(0)
	v_mfma_f32_16x16x32_bf16 v[8:11], v[12:15], v[92:95], v[8:11]
	ds_read_b128 v[12:15], v171 offset:256
	v_lshl_add_u64 v[162:163], v[162:163], 0, s[44:45]
	s_cmp_eq_u32 s42, 0x20000
	s_waitcnt lgkmcnt(0)
	v_mfma_f32_16x16x32_bf16 v[4:7], v[12:15], v[98:101], v[4:7]
	ds_read_b128 v[12:15], v171 offset:320
	v_mov_b64_e32 v[134:135], v[130:131]
	s_waitcnt lgkmcnt(0)
	v_mfma_f32_16x16x32_bf16 v[8:11], v[12:15], v[102:105], v[8:11]
	ds_read_b128 v[12:15], v171 offset:384
	s_waitcnt lgkmcnt(0)
	v_mfma_f32_16x16x32_bf16 v[4:7], v[12:15], v[106:109], v[4:7]
	ds_read_b128 v[12:15], v171 offset:448
	s_waitcnt lgkmcnt(0)
	v_mfma_f32_16x16x32_bf16 v[8:11], v[12:15], v[110:113], v[8:11]
	s_nop 7
	v_add_f32_e32 v4, v4, v8
	v_add_u32_e32 v8, 0x400, v174
	ds_read2_b32 v[12:13], v8 offset1:16
	s_waitcnt lgkmcnt(0)
	v_fmac_f32_e32 v4, v178, v12
	v_mul_f32_e32 v8, 0x3d372713, v4
	v_mul_f32_e32 v8, v4, v8
	v_fma_f32 v8, v4, v8, v4
	v_mul_f32_e32 v8, 0x3f4c422a, v8
	v_add_f32_e32 v8, v8, v8
	v_mul_f32_e32 v8, 0xbfb8aa3b, v8
	v_exp_f32_e32 v8, v8
	s_nop 0
	v_add_f32_e32 v8, 1.0, v8
	v_rcp_f32_e32 v8, v8
	s_nop 0
	v_mul_f32_e32 v4, v4, v8
	v_cvt_pk_bf16_f32 v4, v4, s0
	global_store_short v[0:1], v4, off nt sc1
	v_add_f32_e32 v4, v5, v9
	v_fmac_f32_e32 v4, v178, v13
	v_mul_f32_e32 v5, 0x3d372713, v4
	v_mul_f32_e32 v5, v4, v5
	v_fma_f32 v5, v4, v5, v4
	v_mul_f32_e32 v5, 0x3f4c422a, v5
	v_add_f32_e32 v5, v5, v5
	v_mul_f32_e32 v5, 0xbfb8aa3b, v5
	v_exp_f32_e32 v5, v5
	s_nop 0
	v_add_f32_e32 v5, 1.0, v5
	v_rcp_f32_e32 v5, v5
	s_nop 0
	v_mul_f32_e32 v4, v4, v5
	ds_read_b32 v5, v174 offset:1152
	v_cvt_pk_bf16_f32 v4, v4, s0
	global_store_short v[0:1], v4, off offset:512 nt sc1
	v_add_f32_e32 v4, v6, v10
	s_waitcnt lgkmcnt(0)
	v_fmac_f32_e32 v4, v178, v5
	v_mul_f32_e32 v5, 0x3d372713, v4
	v_mul_f32_e32 v5, v4, v5
	v_fma_f32 v5, v4, v5, v4
	v_mul_f32_e32 v5, 0x3f4c422a, v5
	v_add_f32_e32 v5, v5, v5
	v_mul_f32_e32 v5, 0xbfb8aa3b, v5
	v_exp_f32_e32 v5, v5
	s_nop 0
	v_add_f32_e32 v5, 1.0, v5
	v_rcp_f32_e32 v5, v5
	s_nop 0
	v_mul_f32_e32 v4, v4, v5
	v_cvt_pk_bf16_f32 v4, v4, s0
	global_store_short v[0:1], v4, off offset:1024 nt sc1
	ds_read_b32 v1, v177 offset:1024
	v_add_f32_e32 v0, v7, v11
	s_waitcnt lgkmcnt(0)
	v_fmac_f32_e32 v0, v178, v1
	v_mul_f32_e32 v1, 0x3d372713, v0
	v_mul_f32_e32 v1, v0, v1
	v_fma_f32 v1, v0, v1, v0
	v_mul_f32_e32 v1, 0x3f4c422a, v1
	v_add_f32_e32 v1, v1, v1
	v_mul_f32_e32 v1, 0xbfb8aa3b, v1
	v_exp_f32_e32 v1, v1
	s_nop 0
	v_add_f32_e32 v1, 1.0, v1
	v_rcp_f32_e32 v1, v1
	s_nop 0
	v_mul_f32_e32 v0, v0, v1
	v_cvt_pk_bf16_f32 v4, v0, s0
	v_add_co_u32_e32 v0, vcc, s1, v2
	s_nop 1
	v_addc_co_u32_e32 v1, vcc, 0, v3, vcc
	global_store_short v[0:1], v4, off nt sc1
	s_waitcnt lgkmcnt(0)
	s_cbranch_scc1 .LBB0_101

; __device__ __forceinline__ float sigm(float v) { return __builtin_amdgcn_rcpf(1.0f + __builtin_amdgcn_exp2f(-LOG2E * v)); }
; template <bool PASS2> __device__ __forceinline__ void ssm2_pass(const Ctx& c, int l) {
;     ...
;                         float nr = arA * xAr - aiA * xAi + D0[r], ni = arA * xAi + aiA * xAr + D2[r]; xAr = nr; xAi = ni;
;                         nr = arB * xBr - aiB * xBi + D1[r]; ni = arB * xBi + aiB * xBr + D3[r]; xBr = nr; xBi = ni;
;                         if (PASS2) { if (hi == ps) { const int row = (8 * gq + 4 * ps + i) & 15;
;                             const unsigned hr = pk_bf16(xAr, xBr), hm = pk_bf16(xAi, xBi);
;                             const unsigned lr = pk_bf16(xAr - bf_lo(hr), xBr - bf_hi(hr)), lm = pk_bf16(xAi - bf_lo(hm), xBi - bf_hi(hm));
;                             XP[row * 132 + q] = (hr & 0xffffu) | (lr << 16); XP[row * 132 + 32 + q] = (hr >> 16) | (lr & 0xffff0000u);
;                             XP[row * 132 + 64 + q] = (hm & 0xffffu) | (lm << 16); XP[row * 132 + 96 + q] = (hm >> 16) | (lm & 0xffff0000u); } } }
;                     xAr = half_bcast(xAr, ps); xAi = half_bcast(xAi, ps); xBr = half_bcast(xBr, ps); xBi = half_bcast(xBi, ps);
;                 }
;                 if (PASS2 && (gq & 1)) {
;                     LDS_FENCE();
;                     f32x4 a0 = {0.f, 0.f, 0.f, 0.f}, a1 = {0.f, 0.f, 0.f, 0.f};
;                     const unsigned* xp = XP + (lane & 15) * 132 + 4 * (lane >> 4);
; #pragma unroll
;                     for (int s_ = 0; s_ < 8; s_ += 2) {
;                         a0 = __builtin_amdgcn_mfma_f32_16x16x32_bf16(*(const bf16x8*)(xp + 16 * s_), Cb[s_], a0, 0, 0, 0);
;                         a1 = __builtin_amdgcn_mfma_f32_16x16x32_bf16(*(const bf16x8*)(xp + 16 * s_ + 16), Cb[s_ + 1], a1, 0, 0, 0);
;                     }
;                     const int h = lane & 15, t16 = (gq >> 1) * 16;
; #pragma unroll
;                     for (int i = 0; i < 4; ++i) { const int tt = 4 * (lane >> 4) + i;
;                         float y = a0[i] + a1[i] + dsk * Ul[(t16 + tt) * 16 + h];
;                         const float z = 0.7978845608028654f * (y + 0.044715f * y * y * y);
;                         y = y * sigm(2.0f * z);
;                         YG[(row0 + blk * 32 + t16 + tt) * 256 + g * 16 + h] = (bf16_t)(pk_bf16(y, 0.f) & 0xffffu); }
;                     LDS_FENCE();
.LBB0_159:
	s_or_b64 exec, exec, s[44:45]
	v_mov_b32_e32 v4, v0
	v_mov_b32_e32 v6, v2
	v_mov_b32_e32 v5, v1
	v_mov_b32_e32 v7, v3
	v_permlane32_swap_b32_e32 v0, v4
	v_permlane32_swap_b32_e32 v2, v6
	v_permlane32_swap_b32_e32 v1, v5
	v_permlane32_swap_b32_e32 v3, v7
	s_waitcnt lgkmcnt(0)
	ds_read_b128 v[0:3], v171
	ds_read_b128 v[16:19], v171 offset:64
	ds_read_b128 v[20:23], v171 offset:128
	s_waitcnt lgkmcnt(2)
	v_mfma_f32_16x16x32_bf16 v[0:3], v[0:3], v[80:83], 0
	s_waitcnt lgkmcnt(0)
	v_mfma_f32_16x16x32_bf16 v[0:3], v[20:23], v[88:91], v[0:3]
	ds_read_b128 v[20:23], v171 offset:192
	v_mfma_f32_16x16x32_bf16 v[16:19], v[16:19], v[84:87], 0
	s_waitcnt lgkmcnt(0)
	v_mfma_f32_16x16x32_bf16 v[16:19], v[20:23], v[92:95], v[16:19]
	ds_read_b128 v[20:23], v171 offset:256
	s_waitcnt lgkmcnt(0)
	v_mfma_f32_16x16x32_bf16 v[0:3], v[20:23], v[98:101], v[0:3]
	ds_read_b128 v[20:23], v171 offset:320
	s_waitcnt lgkmcnt(0)
	v_mfma_f32_16x16x32_bf16 v[16:19], v[20:23], v[102:105], v[16:19]
	ds_read_b128 v[20:23], v171 offset:384
	s_waitcnt lgkmcnt(0)
	v_mfma_f32_16x16x32_bf16 v[20:23], v[20:23], v[106:109], v[0:3]
	s_nop 2
	ds_read_b128 v[0:3], v171 offset:448
	s_waitcnt lgkmcnt(0)
	v_mfma_f32_16x16x32_bf16 v[16:19], v[0:3], v[110:113], v[16:19]
	ds_read_b32 v1, v174
	s_nop 6
	v_add_f32_e32 v0, v20, v16
	s_waitcnt lgkmcnt(0)
	v_fmac_f32_e32 v0, v178, v1
	v_mul_f32_e32 v1, 0x3d372713, v0
	v_mul_f32_e32 v1, v0, v1
	v_fma_f32 v1, v0, v1, v0
	v_mul_f32_e32 v1, 0x3f4c422a, v1
	v_add_f32_e32 v1, v1, v1
	v_mul_f32_e32 v1, 0xbfb8aa3b, v1
	v_exp_f32_e32 v1, v1
	s_nop 0
	v_add_f32_e32 v1, 1.0, v1
	v_rcp_f32_e32 v1, v1
	s_nop 0
	v_mul_f32_e32 v0, v0, v1
	v_cvt_pk_bf16_f32 v16, v0, s0
	v_lshl_add_u64 v[0:1], v[164:165], 0, s[42:43]
	v_add_co_u32_e32 v2, vcc, s7, v0
	s_nop 1
	v_addc_co_u32_e32 v3, vcc, 0, v1, vcc
	global_store_short v[2:3], v16, off nt sc1
	v_add_f32_e32 v16, v21, v17
	ds_read_b32 v17, v175
	s_waitcnt lgkmcnt(0)
	v_fmac_f32_e32 v16, v178, v17
	v_mul_f32_e32 v17, 0x3d372713, v16
	v_mul_f32_e32 v17, v16, v17
	v_fma_f32 v17, v16, v17, v16
	v_mul_f32_e32 v17, 0x3f4c422a, v17
	v_add_f32_e32 v17, v17, v17
	v_mul_f32_e32 v17, 0xbfb8aa3b, v17
	v_exp_f32_e32 v17, v17
	s_nop 0
	v_add_f32_e32 v17, 1.0, v17
	v_rcp_f32_e32 v17, v17
	s_nop 0
	v_mul_f32_e32 v16, v16, v17
	ds_read_b32 v17, v176
	v_cvt_pk_bf16_f32 v16, v16, s0
	global_store_short v[2:3], v16, off offset:512 nt sc1
	v_add_f32_e32 v16, v22, v18
	s_waitcnt lgkmcnt(0)
	v_fmac_f32_e32 v16, v178, v17
	v_mul_f32_e32 v17, 0x3d372713, v16
	v_mul_f32_e32 v17, v16, v17
	v_fma_f32 v17, v16, v17, v16
	v_mul_f32_e32 v17, 0x3f4c422a, v17
	v_add_f32_e32 v17, v17, v17
	v_mul_f32_e32 v17, 0xbfb8aa3b, v17
	v_exp_f32_e32 v17, v17
	s_nop 0
	v_add_f32_e32 v17, 1.0, v17
	v_rcp_f32_e32 v17, v17
	s_nop 0
	v_mul_f32_e32 v16, v16, v17
	v_cvt_pk_bf16_f32 v16, v16, s0
	global_store_short v[2:3], v16, off offset:1024 nt sc1
	ds_read_b32 v3, v177
	v_add_f32_e32 v2, v23, v19
	s_waitcnt lgkmcnt(0)
	v_fmac_f32_e32 v2, v178, v3
	v_mul_f32_e32 v3, 0x3d372713, v2
	v_mul_f32_e32 v3, v2, v3
	v_fma_f32 v3, v2, v3, v2
	v_mul_f32_e32 v3, 0x3f4c422a, v3
	v_add_f32_e32 v3, v3, v3
	v_mul_f32_e32 v3, 0xbfb8aa3b, v3
	v_exp_f32_e32 v3, v3
	s_nop 0
	v_add_f32_e32 v3, 1.0, v3
	v_rcp_f32_e32 v3, v3
	s_nop 0
	v_mul_f32_e32 v2, v2, v3
	v_cvt_pk_bf16_f32 v18, v2, s0
	v_lshl_add_u64 v[2:3], v[160:161], 0, s[42:43]
	v_add_co_u32_e32 v16, vcc, s7, v2
	s_nop 1
	v_addc_co_u32_e32 v17, vcc, 0, v3, vcc
	global_store_short v[16:17], v18, off nt sc1
	s_waitcnt lgkmcnt(0)
	v_pk_mul_f32 v[18:19], v[158:159], v[6:7]
	v_pk_mul_f32 v[6:7], v[156:157], v[6:7]
	v_mov_b32_e32 v16, v56
	v_mov_b32_e32 v17, v8
	v_pk_fma_f32 v[18:19], v[156:157], v[4:5], v[18:19] neg_lo:[0,0,1] neg_hi:[0,0,1]
	v_pk_fma_f32 v[6:7], v[158:159], v[4:5], v[6:7]
	v_mov_b32_e32 v4, v40
	v_mov_b32_e32 v5, v24
	v_pk_add_f32 v[18:19], v[16:17], v[18:19]
	v_pk_add_f32 v[6:7], v[4:5], v[6:7]
	s_and_saveexec_b64 s[44:45], s[38:39]
	s_cbranch_execz .LBB0_161
	v_cvt_pk_bf16_f32 v8, v18, v19
	v_lshlrev_b32_e32 v20, 16, v8
	v_and_b32_e32 v21, 0xffff0000, v8
	v_cvt_pk_bf16_f32 v22, v6, v7
	v_pk_add_f32 v[20:21], v[18:19], v[20:21] neg_lo:[0,1] neg_hi:[0,1]
	s_nop 0
	v_cvt_pk_bf16_f32 v23, v20, v21
	v_lshlrev_b32_e32 v20, 16, v22
	v_and_b32_e32 v21, 0xffff0000, v22
	v_pk_add_f32 v[20:21], v[6:7], v[20:21] neg_lo:[0,1] neg_hi:[0,1]
	s_nop 0
	v_cvt_pk_bf16_f32 v20, v20, v21
	v_and_b32_e32 v21, 0xffff, v8
	v_lshrrev_b32_e32 v8, 16, v8
	v_lshl_or_b32 v21, v23, 16, v21
	v_and_or_b32 v8, v23, s59, v8
	ds_write2_b32 v172, v21, v8 offset1:32
	v_and_b32_e32 v8, 0xffff, v22
	v_lshrrev_b32_e32 v21, 16, v22
	v_lshl_or_b32 v8, v20, 16, v8
	v_and_or_b32 v20, v20, s59, v21
	ds_write2_b32 v172, v8, v20 offset0:64 offset1:96

; __device__ __forceinline__ void pool_tile(const Ctx& c, int l, int tile) {
;     ...
;             f32x16 acc = {};
; #pragma unroll 8
;             for (int s = 0; s < 32; ++s) {
;                 const float a = Pm[(32 * rt + li) * 65 + 2 * s + lh];
;                 const float b = pw[(size_t)(2 * s + lh) * 64];
;                 acc = __builtin_amdgcn_mfma_f32_32x32x2f32(a, b, acc, 0, 0, 0);
;             }
.LBB0_353:
	v_lshl_add_u64 v[144:145], v[110:111], 0, s[68:69]
	global_load_dword v113, v[144:145], off
	global_load_dword v148, v[144:145], off offset:512
	global_load_dword v149, v[144:145], off offset:1024
	global_load_dword v150, v[144:145], off offset:1536
	global_load_dword v151, v[144:145], off offset:2048
	ds_read2_b32 v[146:147], v112 offset1:2
	global_load_dword v152, v[144:145], off offset:2560
	global_load_dword v153, v[144:145], off offset:3072
	global_load_dword v154, v[144:145], off offset:3584
	ds_read2_b32 v[144:145], v112 offset0:4 offset1:6
	s_add_u32 s68, s68, 0x1000
	s_addc_u32 s69, s69, 0
	s_cmpk_eq_i32 s68, 0x4000
	s_waitcnt vmcnt(7) lgkmcnt(1)
	v_mfma_f32_32x32x2_f32 v[0:15], v146, v113, v[0:15]
	s_waitcnt vmcnt(6)
	v_mfma_f32_32x32x2_f32 v[0:15], v147, v148, v[0:15]
	s_waitcnt vmcnt(5) lgkmcnt(0)
	v_mfma_f32_32x32x2_f32 v[0:15], v144, v149, v[0:15]
	s_waitcnt vmcnt(4)
	v_mfma_f32_32x32x2_f32 v[0:15], v145, v150, v[0:15]
	ds_read2_b32 v[144:145], v112 offset0:8 offset1:10
	s_waitcnt vmcnt(3) lgkmcnt(0)
	v_mfma_f32_32x32x2_f32 v[0:15], v144, v151, v[0:15]
	s_waitcnt vmcnt(2)
	v_mfma_f32_32x32x2_f32 v[0:15], v145, v152, v[0:15]
	ds_read2_b32 v[144:145], v112 offset0:12 offset1:14
	v_add_u32_e32 v112, 64, v112
	s_waitcnt vmcnt(1) lgkmcnt(0)
	v_mfma_f32_32x32x2_f32 v[0:15], v144, v153, v[0:15]
	s_waitcnt vmcnt(0)
	v_mfma_f32_32x32x2_f32 v[0:15], v145, v154, v[0:15]
	s_cbranch_scc0 .LBB0_353
; __device__ __forceinline__ float silu_f(float v) { return v * __builtin_amdgcn_rcpf(1.0f + __builtin_amdgcn_exp2f(-1.4426950408889634f * v)); }
; __device__ __forceinline__ unsigned pk_bf16(float lo, float hi) { return pg8::cvt_pk_bf16(lo, hi); }
; __device__ __forceinline__ void pool_tile(const Ctx& c, int l, int tile) {
;     ...
; #pragma unroll
;             for (int r = 0; r < 16; ++r) {
;                 const int i = (r & 3) + 8 * (r >> 2) + 4 * lh; const size_t tok = (size_t)(t0 + 32 * rt + i);
;                 const float v = acc[r] * sc * silu_f(__uint_as_float((unsigned)gv[r] << 16));
;                 Y[tok * 1024 + gi * 64 + j] = (bf16_t)(pk_bf16(v, 0.f) & 0xffffu);
;             }
;         }
;         __syncthreads();
	v_lshlrev_b32_e32 v143, 16, v143
	v_mul_f32_e32 v144, 0xbfb8aa3b, v143
	v_exp_f32_e32 v144, v144
	s_lshl_b32 s34, s16, 1
	s_nop 12
	v_mul_f32_e32 v0, v129, v0
	v_lshl_add_u64 v[112:113], v[34:35], 0, s[34:35]
	v_add_f32_e32 v144, 1.0, v144
	v_rcp_f32_e32 v144, v144
	s_add_i32 s13, s13, 1
	v_lshl_add_u64 v[110:111], v[110:111], 0, s[96:97]
	s_cmp_eq_u32 s13, 4
	v_mul_f32_e32 v143, v144, v143
	v_mul_f32_e32 v0, v143, v0
	v_cvt_pk_bf16_f32 v0, v0, s0
	v_lshl_add_u64 v[144:145], v[112:113], 0, v[76:77]
	global_store_short v[144:145], v0, off nt sc1
	v_mul_f32_e32 v0, v129, v1
	v_lshlrev_b32_e32 v1, 16, v142
	v_mul_f32_e32 v142, 0xbfb8aa3b, v1
	v_exp_f32_e32 v142, v142
	s_nop 0
	v_add_f32_e32 v142, 1.0, v142
	v_rcp_f32_e32 v142, v142
	s_nop 0
	v_mul_f32_e32 v1, v142, v1
	v_mul_f32_e32 v0, v1, v0
	v_cvt_pk_bf16_f32 v142, v0, s0
	v_lshl_add_u64 v[0:1], v[112:113], 0, v[78:79]
	global_store_short v[0:1], v142, off nt sc1
	v_lshlrev_b32_e32 v1, 16, v141
	v_mul_f32_e32 v0, v129, v2
	v_mul_f32_e32 v2, 0xbfb8aa3b, v1
	v_exp_f32_e32 v2, v2
	s_nop 0
	v_add_f32_e32 v2, 1.0, v2
	v_rcp_f32_e32 v2, v2
	s_nop 0
	v_mul_f32_e32 v1, v2, v1
	v_mul_f32_e32 v0, v1, v0
	v_cvt_pk_bf16_f32 v2, v0, s0
	v_lshl_add_u64 v[0:1], v[112:113], 0, v[80:81]
	global_store_short v[0:1], v2, off nt sc1
	v_lshlrev_b32_e32 v1, 16, v140
	v_mul_f32_e32 v2, 0xbfb8aa3b, v1
	v_exp_f32_e32 v2, v2
	v_mul_f32_e32 v0, v129, v3
	v_add_f32_e32 v2, 1.0, v2
	v_rcp_f32_e32 v2, v2
	s_nop 0
	v_mul_f32_e32 v1, v2, v1
	v_mul_f32_e32 v0, v1, v0
	v_cvt_pk_bf16_f32 v2, v0, s0
	v_lshl_add_u64 v[0:1], v[112:113], 0, v[82:83]
	global_store_short v[0:1], v2, off nt sc1
	v_lshlrev_b32_e32 v1, 16, v139
	v_mul_f32_e32 v2, 0xbfb8aa3b, v1
	v_exp_f32_e32 v2, v2
	v_mul_f32_e32 v0, v129, v4
	v_add_f32_e32 v2, 1.0, v2
	v_rcp_f32_e32 v2, v2
	s_nop 0
	v_mul_f32_e32 v1, v2, v1
	v_mul_f32_e32 v0, v1, v0
	v_cvt_pk_bf16_f32 v2, v0, s0
	v_lshl_add_u64 v[0:1], v[112:113], 0, v[84:85]
	global_store_short v[0:1], v2, off nt sc1
	v_lshlrev_b32_e32 v1, 16, v138
	v_mul_f32_e32 v2, 0xbfb8aa3b, v1
	v_exp_f32_e32 v2, v2
	v_mul_f32_e32 v0, v129, v5
	v_add_f32_e32 v2, 1.0, v2
	v_rcp_f32_e32 v2, v2
	s_nop 0
	v_mul_f32_e32 v1, v2, v1
	v_mul_f32_e32 v0, v1, v0
	v_cvt_pk_bf16_f32 v2, v0, s0
	v_lshl_add_u64 v[0:1], v[112:113], 0, v[86:87]
	global_store_short v[0:1], v2, off nt sc1
	v_lshlrev_b32_e32 v1, 16, v137
	v_mul_f32_e32 v2, 0xbfb8aa3b, v1
	v_exp_f32_e32 v2, v2
	v_mul_f32_e32 v0, v129, v6
	v_add_f32_e32 v2, 1.0, v2
	v_rcp_f32_e32 v2, v2
	s_nop 0
	v_mul_f32_e32 v1, v2, v1
	v_mul_f32_e32 v0, v1, v0
	v_cvt_pk_bf16_f32 v2, v0, s0
	v_lshl_add_u64 v[0:1], v[112:113], 0, v[88:89]
	global_store_short v[0:1], v2, off nt sc1
	v_lshlrev_b32_e32 v1, 16, v136
	v_mul_f32_e32 v2, 0xbfb8aa3b, v1
	v_exp_f32_e32 v2, v2
	v_mul_f32_e32 v0, v129, v7
	v_add_f32_e32 v2, 1.0, v2
	v_rcp_f32_e32 v2, v2
	s_nop 0
	v_mul_f32_e32 v1, v2, v1
	v_mul_f32_e32 v0, v1, v0
	v_cvt_pk_bf16_f32 v2, v0, s0
	v_lshl_add_u64 v[0:1], v[112:113], 0, v[90:91]
	global_store_short v[0:1], v2, off nt sc1
	v_lshlrev_b32_e32 v1, 16, v135
	v_mul_f32_e32 v2, 0xbfb8aa3b, v1
	v_exp_f32_e32 v2, v2
	v_mul_f32_e32 v0, v129, v8
	v_add_f32_e32 v2, 1.0, v2
	v_rcp_f32_e32 v2, v2
	s_nop 0
	v_mul_f32_e32 v1, v2, v1
	v_mul_f32_e32 v0, v1, v0
	v_cvt_pk_bf16_f32 v2, v0, s0
	v_lshl_add_u64 v[0:1], v[112:113], 0, v[92:93]
	global_store_short v[0:1], v2, off nt sc1
	v_lshlrev_b32_e32 v1, 16, v134
	v_mul_f32_e32 v2, 0xbfb8aa3b, v1
	v_exp_f32_e32 v2, v2
	v_mul_f32_e32 v0, v129, v9
	v_add_f32_e32 v2, 1.0, v2
	v_rcp_f32_e32 v2, v2
	s_nop 0
	v_mul_f32_e32 v1, v2, v1
	v_mul_f32_e32 v0, v1, v0
	v_cvt_pk_bf16_f32 v2, v0, s0
	v_lshl_add_u64 v[0:1], v[112:113], 0, v[94:95]
	global_store_short v[0:1], v2, off nt sc1
	v_lshlrev_b32_e32 v1, 16, v133
	v_mul_f32_e32 v2, 0xbfb8aa3b, v1
	v_exp_f32_e32 v2, v2
	v_mul_f32_e32 v0, v129, v10
	v_add_f32_e32 v2, 1.0, v2
	v_rcp_f32_e32 v2, v2
	s_nop 0
	v_mul_f32_e32 v1, v2, v1
	v_mul_f32_e32 v0, v1, v0
	v_cvt_pk_bf16_f32 v2, v0, s0
	v_lshl_add_u64 v[0:1], v[112:113], 0, v[98:99]
	global_store_short v[0:1], v2, off nt sc1
	v_lshlrev_b32_e32 v1, 16, v132
	v_mul_f32_e32 v2, 0xbfb8aa3b, v1
	v_exp_f32_e32 v2, v2
	v_mul_f32_e32 v0, v129, v11
	v_add_f32_e32 v2, 1.0, v2
	v_rcp_f32_e32 v2, v2
	s_nop 0
	v_mul_f32_e32 v1, v2, v1
	v_mul_f32_e32 v0, v1, v0
	v_cvt_pk_bf16_f32 v2, v0, s0
	v_lshl_add_u64 v[0:1], v[112:113], 0, v[100:101]
	global_store_short v[0:1], v2, off nt sc1
	v_lshlrev_b32_e32 v1, 16, v131
	v_mul_f32_e32 v2, 0xbfb8aa3b, v1
	v_exp_f32_e32 v2, v2
	v_mul_f32_e32 v0, v129, v12
	v_add_f32_e32 v2, 1.0, v2
	v_rcp_f32_e32 v2, v2
	s_nop 0
	v_mul_f32_e32 v1, v2, v1
	v_mul_f32_e32 v0, v1, v0
	v_cvt_pk_bf16_f32 v2, v0, s0
	v_lshl_add_u64 v[0:1], v[112:113], 0, v[102:103]
	global_store_short v[0:1], v2, off nt sc1
	v_lshlrev_b32_e32 v1, 16, v130
	v_mul_f32_e32 v2, 0xbfb8aa3b, v1
	v_exp_f32_e32 v2, v2
	v_mul_f32_e32 v0, v129, v13
	v_add_f32_e32 v2, 1.0, v2
	v_rcp_f32_e32 v2, v2
	s_nop 0
	v_mul_f32_e32 v1, v2, v1
	v_mul_f32_e32 v0, v1, v0
	v_cvt_pk_bf16_f32 v2, v0, s0
	v_lshl_add_u64 v[0:1], v[112:113], 0, v[104:105]
	global_store_short v[0:1], v2, off nt sc1
	v_lshlrev_b32_e32 v1, 16, v128
	v_mul_f32_e32 v2, 0xbfb8aa3b, v1
	v_exp_f32_e32 v2, v2
	v_mul_f32_e32 v0, v129, v14
	v_add_f32_e32 v2, 1.0, v2
	v_rcp_f32_e32 v2, v2
	s_nop 0
	v_mul_f32_e32 v1, v2, v1
	v_mul_f32_e32 v0, v1, v0
	v_cvt_pk_bf16_f32 v2, v0, s0
	v_lshl_add_u64 v[0:1], v[112:113], 0, v[106:107]
	global_store_short v[0:1], v2, off nt sc1
	v_lshlrev_b32_e32 v1, 16, v96
	v_mul_f32_e32 v2, 0xbfb8aa3b, v1
	v_exp_f32_e32 v2, v2
	v_mul_f32_e32 v0, v129, v15
	v_add_f32_e32 v2, 1.0, v2
	v_rcp_f32_e32 v2, v2
	s_nop 0
	v_mul_f32_e32 v1, v2, v1
	v_mul_f32_e32 v0, v1, v0
	v_cvt_pk_bf16_f32 v2, v0, s0
	v_lshl_add_u64 v[0:1], v[112:113], 0, v[108:109]
	global_store_short v[0:1], v2, off nt sc1
	s_barrier
	s_cbranch_scc0 .LBB0_336
	s_branch .LBB0_328
